# RG-LRU item start: cx rows and gate weights loaded in one batch; SWA: next head's Q and gates prefetched during the current head, Q halves loaded together, sink value reused; SB: V fragment reads hois
# speedup vs baseline: 1.0209x; 1.0068x over previous
; template <int APPLY>
; __device__ void lru_item(PP p, int l, int bb, int ck, int nb, unsigned epoch) {
;     ...
;   __syncthreads();
;   bf16_t cgv[16];
;   if (APPLY) {
;     const int ch = tid & 63, seg = tid >> 6;
; #pragma unroll
;     for (int i = 0; i < 16; ++i) cgv[i] = p->proj[(row0 + seg * 16 + i) * INW + C_CG + nb * 64 + ch];
;   }
;   if (APPLY == 1) {
;     const int ch = tid & 63, w = tid >> 6;
;     const int lo = (ck * w) >> 3, hi = (ck * (w + 1)) >> 3;
;     const float* pa = p->lruA + (long)(bb * 64) * 512 + nb * 64 + ch;
;     const float* ph = p->lruH + (long)(bb * 64) * 512 + nb * 64 + ch;
;     float av[8], hv[8];
; #pragma unroll
;     for (int i = 0; i < 8; ++i) { const bool ok = lo + i < hi; av[i] = ok ? pa[(lo + i) * 512] : 1.0f; hv[i] = ok ? ph[(lo + i) * 512] : 0.0f; }
;     float Ap = 1.f, Hp = 0.f;
; #pragma unroll
;     for (int i = 0; i < 8; ++i) { Hp = av[i] * Hp + hv[i]; Ap *= av[i]; }
;     partA[w * 64 + ch] = Ap; partH[w * 64 + ch] = Hp;
;   }
;   for (int s = tid; s < 131 * 8; s += 512) {
;     const int r = s >> 3, cc = s & 7, t = ck * 128 + r - 3;
;     uint4 u = make_uint4(0, 0, 0, 0);
;     if (t >= 0) u = *(const uint4*)(p->proj + ((long)bb * SEQ + t) * INW + C_CX + nb * 64 + cc * 8);
;     *(uint4*)(cxs + r * 64 + cc * 8) = u;
;   }
.LBB0_114:
	s_lshr_b32 s88, s2, 1
	s_cmpk_gt_i32 s2, 0xff
	s_mov_b64 s[4:5], -1
	s_cbranch_scc0 .LBB0_189
	s_cmpk_gt_u32 s2, 0x1ff
	s_cbranch_scc0 .LBB0_179
	s_cmpk_gt_u32 s2, 0x5ff
	s_cbranch_scc0 .LBB0_147
	s_add_i32 s4, s2, 0xfffffa00
	s_lshr_b32 s59, s4, 9
	s_getreg_b32 s4, hwreg(HW_REG_HW_ID, 0, 6)
	s_lshl_b32 s4, s4, 2
	s_and_b32 s4, s4, 0xfc
	s_add_i32 s4, s4, 0
	s_add_i32 s4, s4, 0x21c00
	v_mov_b32_e32 v0, s4
	ds_read_b32 v0, v0
	s_mov_b32 s4, -1
	s_bfe_u32 s58, s2, 0x60003
	s_waitcnt lgkmcnt(1)
	v_mbcnt_lo_u32_b32 v2, s4, 0
	v_mbcnt_hi_u32_b32 v2, s4, v2
	s_waitcnt lgkmcnt(0)
	v_lshl_add_u32 v24, v0, 6, v2
	s_barrier
	s_load_dwordx2 s[66:67], s[0:1], 0xe0
	v_ashrrev_i32_e32 v27, 6, v24
	s_lshl_b32 s8, s59, 13
	s_lshl_b32 s13, s58, 7
	v_lshlrev_b32_e32 v20, 4, v27
	s_or_b32 s86, s13, s8
	s_mov_b32 s87, s93
	v_ashrrev_i32_e32 v21, 31, v20
	v_lshl_add_u64 v[2:3], v[20:21], 0, s[86:87]
	s_waitcnt lgkmcnt(0)
	v_mov_b64_e32 v[4:5], s[66:67]
	s_and_b32 s6, s2, 7
	v_mad_u64_u32 v[4:5], s[4:5], v2, s91, v[4:5]
	v_and_b32_e32 v71, 63, v24
	v_mad_i32_i24 v5, v3, s91, v5
	s_lshl_b32 s52, s6, 7
	s_mov_b32 s53, s93
	v_lshlrev_b32_e32 v18, 1, v71
	v_mov_b32_e32 v19, v1
	v_lshl_add_u64 v[2:3], v[4:5], 0, s[52:53]
	v_lshl_add_u64 v[6:7], v[2:3], 0, v[18:19]
	s_movk_i32 s4, 0x1000
	v_add_co_u32_e32 v2, vcc, s4, v6
	s_movk_i32 s4, 0x6000
	s_nop 0
	v_addc_co_u32_e32 v3, vcc, 0, v7, vcc
	v_add_co_u32_e32 v4, vcc, s4, v6
	s_mov_b32 s4, 0xb000
	s_nop 0
	v_addc_co_u32_e32 v5, vcc, 0, v7, vcc
	v_add_co_u32_e32 v8, vcc, s4, v6
	s_mov_b32 s4, 0xf000
	s_nop 0
	v_addc_co_u32_e32 v9, vcc, 0, v7, vcc
	v_add_co_u32_e32 v10, vcc, s4, v6
	s_mov_b32 s4, 0x14000
	s_nop 0
	v_addc_co_u32_e32 v11, vcc, 0, v7, vcc
	v_add_co_u32_e32 v12, vcc, s4, v6
	s_mov_b32 s4, 0x19000
	s_nop 0
	v_addc_co_u32_e32 v13, vcc, 0, v7, vcc
	v_add_co_u32_e32 v14, vcc, s4, v6
	s_mov_b32 s4, 0x1d000
	s_nop 0
	v_addc_co_u32_e32 v15, vcc, 0, v7, vcc
	v_add_co_u32_e32 v16, vcc, s4, v6
	s_mov_b32 s4, 0x22000
	s_nop 0
	v_addc_co_u32_e32 v17, vcc, 0, v7, vcc
	v_add_co_u32_e32 v22, vcc, s4, v6
	s_mov_b32 s4, 0x26000
	s_nop 0
	v_addc_co_u32_e32 v23, vcc, 0, v7, vcc
	global_load_ushort v19, v[2:3], off offset:3584
	global_load_ushort v72, v[4:5], off offset:2048
	global_load_ushort v70, v[8:9], off offset:512
	global_load_ushort v69, v[10:11], off offset:3072
	global_load_ushort v68, v[12:13], off offset:1536
	global_load_ushort v67, v[14:15], off
	global_load_ushort v66, v[16:17], off offset:2560
	global_load_ushort v65, v[22:23], off offset:1024
	v_add_co_u32_e32 v2, vcc, s4, v6
	s_mov_b32 s4, 0x2b000
	s_nop 0
	v_addc_co_u32_e32 v3, vcc, 0, v7, vcc
	v_add_co_u32_e32 v4, vcc, s4, v6
	s_mov_b32 s4, 0x30000
	s_nop 0
	v_addc_co_u32_e32 v5, vcc, 0, v7, vcc
	v_add_co_u32_e32 v8, vcc, s4, v6
	s_mov_b32 s4, 0x34000
	s_nop 0
	v_addc_co_u32_e32 v9, vcc, 0, v7, vcc
	v_add_co_u32_e32 v10, vcc, s4, v6
	s_mov_b32 s4, 0x39000
	s_nop 0
	v_addc_co_u32_e32 v11, vcc, 0, v7, vcc
	v_add_co_u32_e32 v12, vcc, s4, v6
	s_movk_i32 s4, 0x418
	s_nop 0
	v_addc_co_u32_e32 v13, vcc, 0, v7, vcc
	v_add_co_u32_e32 v14, vcc, 0x3e000, v6
	s_lshl_b32 s89, s6, 6
	s_nop 0
	v_addc_co_u32_e32 v15, vcc, 0, v7, vcc
	v_add_co_u32_e32 v16, vcc, 0x42000, v6
	s_nop 1
	v_addc_co_u32_e32 v17, vcc, 0, v7, vcc
	v_add_co_u32_e32 v22, vcc, 0x47000, v6
	s_nop 1
	v_addc_co_u32_e32 v23, vcc, 0, v7, vcc
	global_load_ushort v64, v[2:3], off offset:3584
	global_load_ushort v63, v[4:5], off offset:2048
	global_load_ushort v62, v[8:9], off offset:512
	global_load_ushort v61, v[10:11], off offset:3072
	global_load_ushort v60, v[12:13], off offset:1536
	global_load_ushort v59, v[14:15], off
	global_load_ushort v58, v[16:17], off offset:2560
	global_load_ushort v21, v[22:23], off offset:1024
	v_cmp_gt_i32_e32 vcc, s4, v24
	s_and_saveexec_b64 s[4:5], vcc
	s_cbranch_execz .LBB0_122
	v_and_b32_e32 v2, 7, v24
	v_lshlrev_b32_e32 v0, 3, v2
	v_lshl_add_u32 v8, v2, 4, 0
	v_lshlrev_b32_e32 v0, 1, v0
	s_lshl_b32 s92, s89, 1
	v_mov_b32_e32 v118, v24
	v_ashrrev_i32_e32 v118, 3, v118
	v_add_u32_e32 v119, s13, v118
	v_lshl_add_u32 v112, v118, 7, v8
	v_mov_b32_e32 v100, 0
	v_mov_b32_e32 v101, 0
	v_mov_b32_e32 v102, 0
	v_mov_b32_e32 v103, 0
	v_cmp_lt_i32_e32 vcc, 2, v119
	s_and_saveexec_b64 s[40:41], vcc
	v_add3_u32 v119, v119, s8, -3
	v_mov_b64_e32 v[116:117], s[66:67]
	v_mad_u64_u32 v[116:117], s[30:31], v119, s91, v[116:117]
	v_lshl_add_u64 v[116:117], v[116:117], 0, s[92:93]
	v_lshl_add_u64 v[116:117], v[116:117], 0, v[0:1]
	v_add_co_u32_e32 v116, vcc, 0x1000, v116
	s_nop 1
	v_addc_co_u32_e32 v117, vcc, 0, v117, vcc
	global_load_dwordx4 v[100:103], v[116:117], off offset:2560
	s_or_b64 exec, exec, s[40:41]
	v_add_u32_e32 v118, 0x200, v24
	v_ashrrev_i32_e32 v118, 3, v118
	v_add_u32_e32 v119, s13, v118
	v_lshl_add_u32 v113, v118, 7, v8
	v_mov_b32_e32 v104, 0
	v_mov_b32_e32 v105, 0
	v_mov_b32_e32 v106, 0
	v_mov_b32_e32 v107, 0
	v_cmp_lt_i32_e32 vcc, 2, v119
	s_and_saveexec_b64 s[40:41], vcc
	v_add3_u32 v119, v119, s8, -3
	v_mov_b64_e32 v[116:117], s[66:67]
	v_mad_u64_u32 v[116:117], s[30:31], v119, s91, v[116:117]
	v_lshl_add_u64 v[116:117], v[116:117], 0, s[92:93]
	v_lshl_add_u64 v[116:117], v[116:117], 0, v[0:1]
	v_add_co_u32_e32 v116, vcc, 0x1000, v116
	s_nop 1
	v_addc_co_u32_e32 v117, vcc, 0, v117, vcc
	global_load_dwordx4 v[104:107], v[116:117], off offset:2560
	s_or_b64 exec, exec, s[40:41]
	v_cmp_gt_i32_e32 vcc, 24, v24
	s_and_saveexec_b64 s[38:39], vcc
	v_add_u32_e32 v118, 0x400, v24
	v_ashrrev_i32_e32 v118, 3, v118
	v_add_u32_e32 v119, s13, v118
	v_lshl_add_u32 v114, v118, 7, v8
	v_mov_b32_e32 v108, 0
	v_mov_b32_e32 v109, 0
	v_mov_b32_e32 v110, 0
	v_mov_b32_e32 v111, 0
	v_cmp_lt_i32_e32 vcc, 2, v119
	s_and_saveexec_b64 s[40:41], vcc
	v_add3_u32 v119, v119, s8, -3
	v_mov_b64_e32 v[116:117], s[66:67]
	v_mad_u64_u32 v[116:117], s[30:31], v119, s91, v[116:117]
	v_lshl_add_u64 v[116:117], v[116:117], 0, s[92:93]
	v_lshl_add_u64 v[116:117], v[116:117], 0, v[0:1]
	v_add_co_u32_e32 v116, vcc, 0x1000, v116
	s_nop 1
	v_addc_co_u32_e32 v117, vcc, 0, v117, vcc
	global_load_dwordx4 v[108:111], v[116:117], off offset:2560
	s_or_b64 exec, exec, s[40:41]
	s_or_b64 exec, exec, s[38:39]
; __device__ __forceinline__ bf16_t f2bf(float f) { return (bf16_t)(cvt_pk_bf16(f, 0.f) & 0xffffu); }
; __device__ __forceinline__ float bf2f(bf16_t b) { return __uint_as_float(((unsigned)b) << 16); }
; template <int APPLY>
; __device__ void lru_item(PP p, int l, int bb, int ck, int nb, unsigned epoch) {
;     ...
;   for (int s = tid; s < 131 * 8; s += 512) {
;     const int r = s >> 3, cc = s & 7, t = ck * 128 + r - 3;
;     uint4 u = make_uint4(0, 0, 0, 0);
;     if (t >= 0) u = *(const uint4*)(p->proj + ((long)bb * SEQ + t) * INW + C_CX + nb * 64 + cc * 8);
;     *(uint4*)(cxs + r * 64 + cc * 8) = u;
;   }
;   {
;     const bf16_t* wsrc = p->lruWT + (long)((l * 8 + nb) * 2) * 4096;
;     const int d = tid >> 3, c8 = (tid & 7) * 8;
;     *(uint4*)(wta + d * 72 + c8) = *(const uint4*)(wsrc + d * 64 + c8);
;     *(uint4*)(wtx + d * 72 + c8) = *(const uint4*)(wsrc + 4096 + d * 64 + c8);
;   }
;   __syncthreads();
;   {
;     const int ch = tid & 63, gch = nb * 64 + ch;
;     const float* cw = p->conv_w + (long)l * 4 * 512 + gch;
;     const float w0 = cw[0], w1 = cw[512], w2 = cw[1024], w3 = cw[1536], cb = p->conv_b[l * 512 + gch];
; #pragma unroll
;     for (int i = 0; i < 16; ++i) {
;       const int tok = (tid >> 6) + 8 * i;
;       const float v = cb + w0 * bf2f(cxs[(tok + 0) * 64 + ch]) + w1 * bf2f(cxs[(tok + 1) * 64 + ch]) +
;                       w2 * bf2f(cxs[(tok + 2) * 64 + ch]) + w3 * bf2f(cxs[(tok + 3) * 64 + ch]);
;       xcs[tok * 72 + ch] = f2bf(v);
;     }
;   }
.LBB0_122:
	s_or_b64 exec, exec, s[4:5]
	s_load_dwordx4 s[40:43], s[0:1], 0x110
	s_mov_b64 s[4:5], 0x1e00
	v_lshl_add_u64 v[22:23], v[6:7], 0, s[4:5]
	s_lshl_b32 s4, s6, 14
	s_or_b32 s4, s4, s74
	v_ashrrev_i32_e32 v4, 3, v24
	s_waitcnt lgkmcnt(0)
	s_add_u32 s4, s40, s4
	v_lshlrev_b32_e32 v2, 6, v4
	s_addc_u32 s5, s41, 0
	v_ashrrev_i32_e32 v3, 31, v2
	v_lshlrev_b32_e32 v0, 4, v24
	v_lshl_add_u64 v[2:3], v[2:3], 1, s[4:5]
	v_and_b32_e32 v0, 0x70, v0
	s_movk_i32 s8, 0x90
	v_lshl_add_u64 v[6:7], v[2:3], 0, v[0:1]
	v_mul_lo_u32 v2, v4, s8
	v_add3_u32 v0, 0, v2, v0
	global_load_dwordx4 v[120:123], v[6:7], off
	s_movk_i32 s4, 0x2000
	v_or_b32_e32 v8, s89, v71
	s_movk_i32 s6, 0x1000
	v_and_b32_e32 v30, 15, v24
	v_mov_b32_e32 v55, 0x3ecc95a3
	s_mov_b32 s13, 0x7f800000
	v_mov_b32_e32 v57, 0x7f800000
	v_mov_b32_e32 v73, 0x7fc00000
	v_mov_b32_e32 v74, 0xff800000
	s_mov_b32 s30, 0x33800000
	s_mov_b32 s31, 0xf800000
	v_mov_b32_e32 v56, 0x260
	v_add_co_u32_e32 v2, vcc, s4, v6
	s_nop 1
	v_addc_co_u32_e32 v3, vcc, 0, v7, vcc
	global_load_dwordx4 v[124:127], v[2:3], off
	s_waitcnt vmcnt(0)
	ds_write_b128 v112, v[100:103]
	ds_write_b128 v113, v[104:107]
	v_cmp_gt_i32_e32 vcc, 24, v24
	s_and_saveexec_b64 s[38:39], vcc
	ds_write_b128 v114, v[108:111]
	s_or_b64 exec, exec, s[38:39]
	ds_write_b128 v0, v[120:123] offset:35328
	ds_write_b128 v0, v[124:127] offset:44544
	s_waitcnt lgkmcnt(0)
	s_barrier
	s_load_dwordx4 s[44:47], s[0:1], 0x38
	s_load_dwordx2 s[56:57], s[0:1], 0x50
	s_load_dwordx2 s[48:49], s[0:1], 0x60
	s_load_dwordx2 s[50:51], s[0:1], 0xf8
	v_lshlrev_b32_e32 v0, 2, v8
	s_waitcnt lgkmcnt(0)
	s_add_u32 s40, s44, s78
	s_addc_u32 s41, s45, 0
	v_lshl_add_u64 v[2:3], s[40:41], 0, v[0:1]
	global_load_dword v7, v0, s[40:41]
	global_load_dword v5, v0, s[40:41] offset:2048
	v_add_co_u32_e32 v2, vcc, s6, v2
	v_or_b32_e32 v0, s60, v8
	s_nop 0
	v_addc_co_u32_e32 v3, vcc, 0, v3, vcc
	v_lshlrev_b32_e32 v0, 2, v0
	global_load_dword v6, v[2:3], off
	global_load_dword v4, v[2:3], off offset:2048
	global_load_dword v8, v0, s[46:47]
	v_lshlrev_b32_e32 v2, 1, v24
	v_add_u32_e32 v0, 0, v18
	v_and_b32_e32 v2, 0xffffff80, v2
	v_add_u32_e32 v3, v0, v2
	ds_read_u16 v3, v3
	v_add3_u32 v2, 0, v2, v18
	ds_read_u16 v9, v2 offset:128
	s_waitcnt lgkmcnt(1)
	v_lshlrev_b32_e32 v3, 16, v3
	s_waitcnt lgkmcnt(0)
	v_lshlrev_b32_e32 v9, 16, v9
	s_waitcnt vmcnt(0)
	v_fma_f32 v3, v7, v3, v8
	v_fmac_f32_e32 v3, v5, v9
	ds_read_u16 v9, v2 offset:256
	ds_read_u16 v2, v2 offset:384
	s_waitcnt lgkmcnt(1)
	v_lshlrev_b32_e32 v9, 16, v9
	v_fmac_f32_e32 v3, v6, v9
	s_waitcnt lgkmcnt(0)
	v_lshlrev_b32_e32 v2, 16, v2
	v_fmac_f32_e32 v3, v4, v2
	v_cvt_pk_bf16_f32 v9, v3, s0
	v_mad_u64_u32 v[2:3], s[4:5], v27, s8, v[0:1]
	v_lshlrev_b32_e32 v3, 7, v27
	ds_write_b16 v2, v9 offset:16896
	v_add_u32_e32 v9, 0x400, v3
	v_add_u32_e32 v10, v0, v9
	ds_read_u16 v10, v10
	v_add3_u32 v9, 0, v9, v18
	ds_read_u16 v11, v9 offset:128
	s_mov_b32 s5, 0x3f2aaaab
	s_movk_i32 s4, 0x300
	s_waitcnt lgkmcnt(1)
	v_lshlrev_b32_e32 v10, 16, v10
	v_fma_f32 v10, v7, v10, v8
	s_waitcnt lgkmcnt(0)
	v_lshlrev_b32_e32 v11, 16, v11
	v_fmac_f32_e32 v10, v5, v11
	ds_read_u16 v11, v9 offset:256
	ds_read_u16 v9, v9 offset:384
	s_waitcnt lgkmcnt(1)
	v_lshlrev_b32_e32 v11, 16, v11
	v_fmac_f32_e32 v10, v6, v11
	s_waitcnt lgkmcnt(0)
	v_lshlrev_b32_e32 v9, 16, v9
	v_fmac_f32_e32 v10, v4, v9
	v_cvt_pk_bf16_f32 v9, v10, s0
	ds_write_b16 v2, v9 offset:18048
	v_add_u32_e32 v9, 0x800, v3
	v_add_u32_e32 v10, v0, v9
	ds_read_u16 v10, v10
	v_add3_u32 v9, 0, v9, v18
	ds_read_u16 v11, v9 offset:128
	s_waitcnt lgkmcnt(1)
	v_lshlrev_b32_e32 v10, 16, v10
	v_fma_f32 v10, v7, v10, v8
	s_waitcnt lgkmcnt(0)
	v_lshlrev_b32_e32 v11, 16, v11
	v_fmac_f32_e32 v10, v5, v11
	ds_read_u16 v11, v9 offset:256
	ds_read_u16 v9, v9 offset:384
	s_waitcnt lgkmcnt(1)
	v_lshlrev_b32_e32 v11, 16, v11
	v_fmac_f32_e32 v10, v6, v11
	s_waitcnt lgkmcnt(0)
	v_lshlrev_b32_e32 v9, 16, v9
	v_fmac_f32_e32 v10, v4, v9
	v_cvt_pk_bf16_f32 v9, v10, s0
	ds_write_b16 v2, v9 offset:19200
	v_add_u32_e32 v9, 0xc00, v3
	v_add_u32_e32 v10, v0, v9
	ds_read_u16 v10, v10
	v_add3_u32 v9, 0, v9, v18
	ds_read_u16 v11, v9 offset:128
	s_waitcnt lgkmcnt(1)
	v_lshlrev_b32_e32 v10, 16, v10
	v_fma_f32 v10, v7, v10, v8
	s_waitcnt lgkmcnt(0)
	v_lshlrev_b32_e32 v11, 16, v11
	v_fmac_f32_e32 v10, v5, v11
	ds_read_u16 v11, v9 offset:256
	ds_read_u16 v9, v9 offset:384
	s_waitcnt lgkmcnt(1)
	v_lshlrev_b32_e32 v11, 16, v11
	v_fmac_f32_e32 v10, v6, v11
	s_waitcnt lgkmcnt(0)
	v_lshlrev_b32_e32 v9, 16, v9
	v_fmac_f32_e32 v10, v4, v9
	v_cvt_pk_bf16_f32 v9, v10, s0
	ds_write_b16 v2, v9 offset:20352
	v_add_u32_e32 v9, 0x1000, v3
	v_add_u32_e32 v10, v0, v9
	ds_read_u16 v10, v10
	v_add3_u32 v9, 0, v9, v18
	ds_read_u16 v11, v9 offset:128
	s_waitcnt lgkmcnt(1)
	v_lshlrev_b32_e32 v10, 16, v10
	v_fma_f32 v10, v7, v10, v8
	s_waitcnt lgkmcnt(0)
	v_lshlrev_b32_e32 v11, 16, v11
	v_fmac_f32_e32 v10, v5, v11
	ds_read_u16 v11, v9 offset:256
	ds_read_u16 v9, v9 offset:384
	s_waitcnt lgkmcnt(1)
	v_lshlrev_b32_e32 v11, 16, v11
	v_fmac_f32_e32 v10, v6, v11
	s_waitcnt lgkmcnt(0)
	v_lshlrev_b32_e32 v9, 16, v9
	v_fmac_f32_e32 v10, v4, v9
	v_cvt_pk_bf16_f32 v9, v10, s0
	ds_write_b16 v2, v9 offset:21504
	v_add_u32_e32 v9, 0x1400, v3
	v_add_u32_e32 v10, v0, v9
	ds_read_u16 v10, v10
	v_add3_u32 v9, 0, v9, v18
	ds_read_u16 v11, v9 offset:128
	s_waitcnt lgkmcnt(1)
	v_lshlrev_b32_e32 v10, 16, v10
	v_fma_f32 v10, v7, v10, v8
	s_waitcnt lgkmcnt(0)
	v_lshlrev_b32_e32 v11, 16, v11
	v_fmac_f32_e32 v10, v5, v11
	ds_read_u16 v11, v9 offset:256
	ds_read_u16 v9, v9 offset:384
	s_waitcnt lgkmcnt(1)
	v_lshlrev_b32_e32 v11, 16, v11
	v_fmac_f32_e32 v10, v6, v11
	s_waitcnt lgkmcnt(0)
; __device__ __forceinline__ bf16_t f2bf(float f) { return (bf16_t)(cvt_pk_bf16(f, 0.f) & 0xffffu); }
; __device__ __forceinline__ float bf2f(bf16_t b) { return __uint_as_float(((unsigned)b) << 16); }
; template <int APPLY>
; __device__ void lru_item(PP p, int l, int bb, int ck, int nb, unsigned epoch) {
;     ...
; #pragma unroll
;     for (int i = 0; i < 16; ++i) {
;       const int tok = (tid >> 6) + 8 * i;
;       const float v = cb + w0 * bf2f(cxs[(tok + 0) * 64 + ch]) + w1 * bf2f(cxs[(tok + 1) * 64 + ch]) +
;                       w2 * bf2f(cxs[(tok + 2) * 64 + ch]) + w3 * bf2f(cxs[(tok + 3) * 64 + ch]);
;       xcs[tok * 72 + ch] = f2bf(v);
;     }
;   }
;   __syncthreads();
	v_lshlrev_b32_e32 v9, 16, v9
	v_fmac_f32_e32 v10, v4, v9
	v_cvt_pk_bf16_f32 v9, v10, s0
	ds_write_b16 v2, v9 offset:22656
	v_add_u32_e32 v9, 0x1800, v3
	v_add_u32_e32 v10, v0, v9
	ds_read_u16 v10, v10
	v_add3_u32 v9, 0, v9, v18
	ds_read_u16 v11, v9 offset:128
	s_waitcnt lgkmcnt(1)
	v_lshlrev_b32_e32 v10, 16, v10
	v_fma_f32 v10, v7, v10, v8
	s_waitcnt lgkmcnt(0)
	v_lshlrev_b32_e32 v11, 16, v11
	v_fmac_f32_e32 v10, v5, v11
	ds_read_u16 v11, v9 offset:256
	ds_read_u16 v9, v9 offset:384
	s_waitcnt lgkmcnt(1)
	v_lshlrev_b32_e32 v11, 16, v11
	v_fmac_f32_e32 v10, v6, v11
	s_waitcnt lgkmcnt(0)
	v_lshlrev_b32_e32 v9, 16, v9
	v_fmac_f32_e32 v10, v4, v9
	v_cvt_pk_bf16_f32 v9, v10, s0
	ds_write_b16 v2, v9 offset:23808
	v_add_u32_e32 v9, 0x1c00, v3
	v_add_u32_e32 v10, v0, v9
	ds_read_u16 v10, v10
	v_add3_u32 v9, 0, v9, v18
	ds_read_u16 v11, v9 offset:128
	s_waitcnt lgkmcnt(1)
	v_lshlrev_b32_e32 v10, 16, v10
	v_fma_f32 v10, v7, v10, v8
	s_waitcnt lgkmcnt(0)
	v_lshlrev_b32_e32 v11, 16, v11
	v_fmac_f32_e32 v10, v5, v11
	ds_read_u16 v11, v9 offset:256
	ds_read_u16 v9, v9 offset:384
	s_waitcnt lgkmcnt(1)
	v_lshlrev_b32_e32 v11, 16, v11
	v_fmac_f32_e32 v10, v6, v11
	s_waitcnt lgkmcnt(0)
	v_lshlrev_b32_e32 v9, 16, v9
	v_fmac_f32_e32 v10, v4, v9
	v_cvt_pk_bf16_f32 v9, v10, s0
	ds_write_b16 v2, v9 offset:24960
	v_add_u32_e32 v9, 0x2000, v3
	v_add_u32_e32 v10, v0, v9
	ds_read_u16 v10, v10
	v_add3_u32 v9, 0, v9, v18
	ds_read_u16 v11, v9 offset:128
	s_waitcnt lgkmcnt(1)
	v_lshlrev_b32_e32 v10, 16, v10
	v_fma_f32 v10, v7, v10, v8
	s_waitcnt lgkmcnt(0)
	v_lshlrev_b32_e32 v11, 16, v11
	v_fmac_f32_e32 v10, v5, v11
	ds_read_u16 v11, v9 offset:256
	ds_read_u16 v9, v9 offset:384
	s_waitcnt lgkmcnt(1)
	v_lshlrev_b32_e32 v11, 16, v11
	v_fmac_f32_e32 v10, v6, v11
	s_waitcnt lgkmcnt(0)
	v_lshlrev_b32_e32 v9, 16, v9
	v_fmac_f32_e32 v10, v4, v9
	v_cvt_pk_bf16_f32 v9, v10, s0
	ds_write_b16 v2, v9 offset:26112
	v_add_u32_e32 v9, 0x2400, v3
	v_add_u32_e32 v10, v0, v9
	ds_read_u16 v10, v10
	v_add3_u32 v9, 0, v9, v18
	ds_read_u16 v11, v9 offset:128
	s_waitcnt lgkmcnt(1)
	v_lshlrev_b32_e32 v10, 16, v10
	v_fma_f32 v10, v7, v10, v8
	s_waitcnt lgkmcnt(0)
	v_lshlrev_b32_e32 v11, 16, v11
	v_fmac_f32_e32 v10, v5, v11
	ds_read_u16 v11, v9 offset:256
	ds_read_u16 v9, v9 offset:384
	s_waitcnt lgkmcnt(1)
	v_lshlrev_b32_e32 v11, 16, v11
	v_fmac_f32_e32 v10, v6, v11
	s_waitcnt lgkmcnt(0)
	v_lshlrev_b32_e32 v9, 16, v9
	v_fmac_f32_e32 v10, v4, v9
	v_cvt_pk_bf16_f32 v9, v10, s0
	ds_write_b16 v2, v9 offset:27264
	v_add_u32_e32 v9, 0x2800, v3
	v_add_u32_e32 v10, v0, v9
	ds_read_u16 v10, v10
	v_add3_u32 v9, 0, v9, v18
	ds_read_u16 v11, v9 offset:128
	s_waitcnt lgkmcnt(1)
	v_lshlrev_b32_e32 v10, 16, v10
	v_fma_f32 v10, v7, v10, v8
	s_waitcnt lgkmcnt(0)
	v_lshlrev_b32_e32 v11, 16, v11
	v_fmac_f32_e32 v10, v5, v11
	ds_read_u16 v11, v9 offset:256
	ds_read_u16 v9, v9 offset:384
	s_waitcnt lgkmcnt(1)
	v_lshlrev_b32_e32 v11, 16, v11
	v_fmac_f32_e32 v10, v6, v11
	s_waitcnt lgkmcnt(0)
	v_lshlrev_b32_e32 v9, 16, v9
	v_fmac_f32_e32 v10, v4, v9
	v_cvt_pk_bf16_f32 v9, v10, s0
	ds_write_b16 v2, v9 offset:28416
	v_add_u32_e32 v9, 0x2c00, v3
	v_add_u32_e32 v10, v0, v9
	ds_read_u16 v10, v10
	v_add3_u32 v9, 0, v9, v18
	ds_read_u16 v11, v9 offset:128
	s_waitcnt lgkmcnt(1)
	v_lshlrev_b32_e32 v10, 16, v10
	v_fma_f32 v10, v7, v10, v8
	s_waitcnt lgkmcnt(0)
	v_lshlrev_b32_e32 v11, 16, v11
	v_fmac_f32_e32 v10, v5, v11
	ds_read_u16 v11, v9 offset:256
	ds_read_u16 v9, v9 offset:384
	s_waitcnt lgkmcnt(1)
	v_lshlrev_b32_e32 v11, 16, v11
	v_fmac_f32_e32 v10, v6, v11
	s_waitcnt lgkmcnt(0)
	v_lshlrev_b32_e32 v9, 16, v9
	v_fmac_f32_e32 v10, v4, v9
	v_cvt_pk_bf16_f32 v9, v10, s0
	ds_write_b16 v2, v9 offset:29568
	v_add_u32_e32 v9, 0x3000, v3
	v_add_u32_e32 v10, v0, v9
	ds_read_u16 v10, v10
	v_add3_u32 v9, 0, v9, v18
	ds_read_u16 v11, v9 offset:128
	s_waitcnt lgkmcnt(1)
	v_lshlrev_b32_e32 v10, 16, v10
	v_fma_f32 v10, v7, v10, v8
	s_waitcnt lgkmcnt(0)
	v_lshlrev_b32_e32 v11, 16, v11
	v_fmac_f32_e32 v10, v5, v11
	ds_read_u16 v11, v9 offset:256
	ds_read_u16 v9, v9 offset:384
	s_waitcnt lgkmcnt(1)
	v_lshlrev_b32_e32 v11, 16, v11
	v_fmac_f32_e32 v10, v6, v11
	s_waitcnt lgkmcnt(0)
	v_lshlrev_b32_e32 v9, 16, v9
	v_fmac_f32_e32 v10, v4, v9
	v_cvt_pk_bf16_f32 v9, v10, s0
	ds_write_b16 v2, v9 offset:30720
	v_add_u32_e32 v9, 0x3400, v3
	v_add_u32_e32 v10, v0, v9
	ds_read_u16 v10, v10
	v_add3_u32 v9, 0, v9, v18
	ds_read_u16 v11, v9 offset:128
	s_waitcnt lgkmcnt(1)
	v_lshlrev_b32_e32 v10, 16, v10
	v_fma_f32 v10, v7, v10, v8
	s_waitcnt lgkmcnt(0)
	v_lshlrev_b32_e32 v11, 16, v11
	v_fmac_f32_e32 v10, v5, v11
	ds_read_u16 v11, v9 offset:256
	ds_read_u16 v9, v9 offset:384
	s_waitcnt lgkmcnt(1)
	v_lshlrev_b32_e32 v11, 16, v11
	v_fmac_f32_e32 v10, v6, v11
	s_waitcnt lgkmcnt(0)
	v_lshlrev_b32_e32 v9, 16, v9
	v_fmac_f32_e32 v10, v4, v9
	v_cvt_pk_bf16_f32 v9, v10, s0
	ds_write_b16 v2, v9 offset:31872
	v_add_u32_e32 v9, 0x3800, v3
	v_add_u32_e32 v10, v0, v9
	ds_read_u16 v10, v10
	v_add3_u32 v9, 0, v9, v18
	ds_read_u16 v11, v9 offset:128
	v_add_u32_e32 v3, 0x3c00, v3
	v_add_u32_e32 v0, v0, v3
	s_waitcnt lgkmcnt(1)
	v_lshlrev_b32_e32 v10, 16, v10
	v_fma_f32 v10, v7, v10, v8
	s_waitcnt lgkmcnt(0)
	v_lshlrev_b32_e32 v11, 16, v11
	v_fmac_f32_e32 v10, v5, v11
	ds_read_u16 v11, v9 offset:256
	ds_read_u16 v9, v9 offset:384
	s_waitcnt lgkmcnt(1)
	v_lshlrev_b32_e32 v11, 16, v11
	v_fmac_f32_e32 v10, v6, v11
	s_waitcnt lgkmcnt(0)
	v_lshlrev_b32_e32 v9, 16, v9
	v_fmac_f32_e32 v10, v4, v9
	v_cvt_pk_bf16_f32 v9, v10, s0
	ds_write_b16 v2, v9 offset:33024
	ds_read_u16 v0, v0
	s_waitcnt lgkmcnt(0)
	v_lshlrev_b32_e32 v0, 16, v0
	v_fmac_f32_e32 v8, v7, v0
	v_add3_u32 v0, 0, v3, v18
	ds_read_u16 v3, v0 offset:128
	s_waitcnt lgkmcnt(0)
	v_lshlrev_b32_e32 v3, 16, v3
	v_fmac_f32_e32 v8, v5, v3
	ds_read_u16 v3, v0 offset:256
	ds_read_u16 v0, v0 offset:384
	s_waitcnt lgkmcnt(1)
	v_lshlrev_b32_e32 v3, 16, v3
	v_fmac_f32_e32 v8, v6, v3
	s_waitcnt lgkmcnt(0)
	v_lshlrev_b32_e32 v0, 16, v0
	v_fmac_f32_e32 v8, v4, v0
	v_cvt_pk_bf16_f32 v0, v8, s0
	ds_write_b16 v2, v0 offset:34176
	v_or_b32_e32 v0, v20, v30
	v_mul_lo_u32 v0, v0, s8
	v_and_b32_e32 v2, 48, v24
	v_add3_u32 v0, 0, v0, v2
	s_waitcnt lgkmcnt(0)
	s_barrier
; __device__ __forceinline__ float bf2f(bf16_t b) { return __uint_as_float(((unsigned)b) << 16); }
; __device__ __forceinline__ float sigmoidf_(float x) { return frcp(1.0f + fexp2(-x * LOG2E)); }
; template <int APPLY>
; __device__ void lru_item(PP p, int l, int bb, int ck, int nb, unsigned epoch) {
;     ...
;   {
;     bf16x8 a[2];
; #pragma unroll
;     for (int ks = 0; ks < 2; ++ks) a[ks] = *(const bf16x8*)(xcs + (wid * 16 + fr) * 72 + ks * 32 + fq * 8);
; #pragma unroll
;     for (int nk = 0; nk < 4; ++nk) {
;       f32x4 ra = f32x4{0.f, 0.f, 0.f, 0.f}, ia = f32x4{0.f, 0.f, 0.f, 0.f};
; #pragma unroll
;       for (int ks = 0; ks < 2; ++ks) {
;         bf16x8 ba = *(const bf16x8*)(wta + (nk * 16 + fr) * 72 + ks * 32 + fq * 8);
;         bf16x8 bx = *(const bf16x8*)(wtx + (nk * 16 + fr) * 72 + ks * 32 + fq * 8);
;         ra = __builtin_amdgcn_mfma_f32_16x16x32_bf16(a[ks], ba, ra, 0, 0, 0);
;         ia = __builtin_amdgcn_mfma_f32_16x16x32_bf16(a[ks], bx, ia, 0, 0, 0);
;       }
;       const int ch = nk * 16 + fr, gch = nb * 64 + ch;
;       const float ba_ = p->lru_b_a[l * 512 + gch], bx_ = p->lru_b_x[l * 512 + gch];
;       const float sp = log1pf(__expf(-p->lru_lambda[l * 512 + gch]));
;       const float* cw = p->conv_w + (long)l * 4 * 512 + gch;
;       const float w0 = cw[0], w1 = cw[512], w2 = cw[1024], w3 = cw[1536], cb = p->conv_b[l * 512 + gch];
; #pragma unroll
;       for (int reg = 0; reg < 4; ++reg) {
;         const int tok = wid * 16 + 4 * fq + reg;
;         const float r = sigmoidf_(ra[reg] + ba_), ig = sigmoidf_(ia[reg] + bx_);
;         const float log_a = -8.0f * r * sp;
;         const float av = __expf(log_a);
;         const float mult = sqrtf(fmaxf(1.0f - __expf(2.0f * log_a), 0.f));
;         const float xc = cb + w0 * bf2f(cxs[(tok + 0) * 64 + ch]) + w1 * bf2f(cxs[(tok + 1) * 64 + ch]) +
;                          w2 * bf2f(cxs[(tok + 2) * 64 + ch]) + w3 * bf2f(cxs[(tok + 3) * 64 + ch]);
;         as_[tok * 64 + ch] = av;
;         bs_[tok * 64 + ch] = mult * ig * xc;
;       }
;     }
;   }
	ds_read_b128 v[6:9], v0 offset:16896
	ds_read_b128 v[2:5], v0 offset:16960
	v_and_b32_e32 v0, 48, v71
	v_add_u32_e32 v34, 0, v0
	v_mul_u32_u24_e32 v0, 0x48, v30
	v_lshl_add_u32 v0, v0, 1, v34
	ds_read_b128 v[10:13], v0 offset:35328
	ds_read_b128 v[14:17], v0 offset:44544
	s_waitcnt lgkmcnt(0)
	v_mfma_f32_16x16x32_bf16 v[36:39], v[6:9], v[14:17], 0
	ds_read_b128 v[14:17], v0 offset:35392
	ds_read_b128 v[40:43], v0 offset:44608
	v_or_b32_e32 v0, s89, v30
	v_or_b32_e32 v25, s60, v0
	v_lshlrev_b32_e32 v25, 2, v25
	global_load_dword v29, v25, s[56:57]
	global_load_dword v28, v25, s[48:49]
	global_load_dword v26, v25, s[50:51]
	v_mfma_f32_16x16x32_bf16 v[10:13], v[6:9], v[10:13], 0
	s_mov_b32 s8, 0x3f317218
	v_lshlrev_b32_e32 v0, 2, v0
	s_waitcnt vmcnt(0)
	s_waitcnt lgkmcnt(1)
	v_mfma_f32_16x16x32_bf16 v[14:17], v[2:5], v[14:17], v[10:13]
	s_waitcnt lgkmcnt(0)
	v_mfma_f32_16x16x32_bf16 v[10:13], v[2:5], v[40:43], v[36:39]
	s_nop 5
	v_add_f32_e32 v14, v14, v29
	v_mul_f32_e32 v14, 0xbfb8aa3b, v14
	v_exp_f32_e32 v14, v14
	s_nop 4
	v_add_f32_e32 v10, v10, v28
	v_lshl_add_u64 v[36:37], s[40:41], 0, v[0:1]
	global_load_dword v39, v0, s[40:41]
	global_load_dword v40, v0, s[40:41] offset:2048
	v_add_f32_e32 v14, 1.0, v14
	v_rcp_f32_e32 v14, v14
	v_mul_f32_e32 v10, 0xbfb8aa3b, v10
	v_mul_f32_e32 v14, 0xc1000000, v14
	v_mov_b32_e32 v33, v26
	v_add_co_u32_e32 v36, vcc, s6, v36
	v_exp_f32_e32 v10, v10
	s_nop 0
	v_addc_co_u32_e32 v37, vcc, 0, v37, vcc
	global_load_dword v42, v[36:37], off
	global_load_dword v41, v[36:37], off offset:2048
	global_load_dword v0, v25, s[46:47]
	v_mul_f32_e32 v25, v14, v33
	v_mul_f32_e32 v14, 0x3fb8aa3b, v25
	v_add_f32_e32 v25, v25, v25
	v_mul_f32_e32 v25, 0x3fb8aa3b, v25
	v_exp_f32_e32 v25, v25
	v_add_f32_e32 v10, 1.0, v10
	v_rcp_f32_e32 v10, v10
	v_exp_f32_e32 v14, v14
	v_sub_f32_e32 v25, 1.0, v25
	v_max_f32_e32 v25, 0, v25
	v_cmp_gt_f32_e32 vcc, s31, v25
	v_mul_f32_e32 v26, 0x4f800000, v25
	v_add_f32_e32 v11, v11, v28
	v_cndmask_b32_e32 v25, v25, v26, vcc
	v_sqrt_f32_e32 v26, v25
	v_mul_f32_e32 v11, 0xbfb8aa3b, v11
	v_exp_f32_e32 v11, v11
	v_add_u32_e32 v31, -1, v26
	v_fma_f32 v32, -v31, v26, v25
	v_cmp_ge_f32_e64 s[38:39], 0, v32
	v_add_u32_e32 v32, 1, v26
	v_add_f32_e32 v11, 1.0, v11
	v_cndmask_b32_e64 v31, v26, v31, s[38:39]
	v_fma_f32 v26, -v32, v26, v25
	v_cmp_lt_f32_e64 s[38:39], 0, v26
	v_rcp_f32_e32 v11, v11
	s_nop 0
	v_cndmask_b32_e64 v26, v31, v32, s[38:39]
	v_mul_f32_e32 v31, 0x37800000, v26
	v_cndmask_b32_e32 v26, v26, v31, vcc
	v_cmp_class_f32_e32 vcc, v25, v56
	s_nop 1
	v_cndmask_b32_e32 v32, v26, v25, vcc
	v_lshlrev_b32_e32 v26, 4, v71
	v_lshlrev_b32_e32 v25, 10, v27
	v_and_or_b32 v38, v26, s4, v25
	v_or_b32_e32 v36, v38, v30
	v_lshlrev_b32_e32 v37, 1, v36
	v_add_u32_e32 v43, 0, v37
	ds_read_u16 v31, v43
	v_lshl_add_u32 v35, v38, 1, 0
	v_add_u32_e32 v37, v43, v37
	ds_write_b32 v37, v14 offset:53760
	v_mul_f32_e32 v10, v10, v32
	s_waitcnt lgkmcnt(1)
	v_lshlrev_b32_e32 v31, 16, v31
	v_lshlrev_b32_e32 v14, 2, v36
	v_readlane_b32 s4, v255, 45
	s_waitcnt vmcnt(0)
	v_fma_f32 v44, v39, v31, v0
	v_lshl_add_u32 v31, v30, 1, v35
	ds_read_u16 v45, v31 offset:128
	ds_read_u16 v46, v31 offset:256
	ds_read_u16 v47, v31 offset:384
	v_add_u32_e32 v32, s4, v14
	s_waitcnt lgkmcnt(2)
	v_lshlrev_b32_e32 v45, 16, v45
	v_fmac_f32_e32 v44, v40, v45
	s_waitcnt lgkmcnt(1)
	v_lshlrev_b32_e32 v46, 16, v46
	v_fmac_f32_e32 v44, v42, v46
	s_waitcnt lgkmcnt(0)
	v_lshlrev_b32_e32 v47, 16, v47
	v_fmac_f32_e32 v44, v41, v47
	v_mul_f32_e32 v10, v44, v10
	ds_write_b32 v32, v10
	v_add_f32_e32 v10, v15, v29
	v_mul_f32_e32 v10, 0xbfb8aa3b, v10
	v_exp_f32_e32 v10, v10
	v_fma_f32 v43, v39, v45, v0
	v_fmac_f32_e32 v43, v40, v46
	v_fmac_f32_e32 v43, v42, v47
	v_add_f32_e32 v10, 1.0, v10
	v_rcp_f32_e32 v10, v10
	s_nop 0
	v_mul_f32_e32 v10, 0xc1000000, v10
	v_mul_f32_e32 v10, v10, v33
	v_mul_f32_e32 v15, 0x3fb8aa3b, v10
	v_add_f32_e32 v10, v10, v10
	v_mul_f32_e32 v10, 0x3fb8aa3b, v10
	v_exp_f32_e32 v10, v10
	v_exp_f32_e32 v15, v15
	v_sub_f32_e32 v10, 1.0, v10
	v_max_f32_e32 v10, 0, v10
	v_cmp_gt_f32_e32 vcc, s31, v10
	v_mul_f32_e32 v32, 0x4f800000, v10
	s_nop 0
	v_cndmask_b32_e32 v10, v10, v32, vcc
	v_sqrt_f32_e32 v32, v10
	s_nop 0
	v_add_u32_e32 v36, -1, v32
	v_fma_f32 v37, -v36, v32, v10
	v_cmp_ge_f32_e64 s[38:39], 0, v37
	v_add_u32_e32 v37, 1, v32
	s_nop 0
	v_cndmask_b32_e64 v36, v32, v36, s[38:39]
	v_fma_f32 v32, -v37, v32, v10
	v_cmp_lt_f32_e64 s[38:39], 0, v32
	s_nop 1
	v_cndmask_b32_e64 v32, v36, v37, s[38:39]
	ds_read_u16 v37, v31 offset:512
	v_mul_f32_e32 v36, 0x37800000, v32
	v_cndmask_b32_e32 v32, v32, v36, vcc
	v_cmp_class_f32_e32 vcc, v10, v56
	v_or_b32_e32 v36, 64, v38
	s_waitcnt lgkmcnt(0)
	v_lshlrev_b32_e32 v44, 16, v37
	v_cndmask_b32_e32 v10, v32, v10, vcc
	v_or_b32_e32 v32, v36, v30
	v_fmac_f32_e32 v43, v41, v44
	v_mul_f32_e32 v10, v11, v10
	v_add_u32_e32 v37, 0, v14
	v_mul_f32_e32 v10, v43, v10
	v_lshl_add_u32 v11, v32, 2, s4
	ds_write_b32 v37, v15 offset:54016
	ds_write_b32 v11, v10
	v_add_f32_e32 v10, v16, v29
	v_mul_f32_e32 v10, 0xbfb8aa3b, v10
	v_exp_f32_e32 v10, v10
	v_add_f32_e32 v11, v12, v28
	v_mul_f32_e32 v11, 0xbfb8aa3b, v11
	v_exp_f32_e32 v11, v11
	v_add_f32_e32 v10, 1.0, v10
	v_rcp_f32_e32 v10, v10
	v_or_b32_e32 v32, 0x80, v38
	v_add_f32_e32 v11, 1.0, v11
	v_rcp_f32_e32 v11, v11
	v_mul_f32_e32 v10, 0xc1000000, v10
	v_mul_f32_e32 v10, v10, v33
	v_mul_f32_e32 v12, 0x3fb8aa3b, v10
	v_add_f32_e32 v10, v10, v10
	v_mul_f32_e32 v10, 0x3fb8aa3b, v10
	v_exp_f32_e32 v10, v10
	v_exp_f32_e32 v12, v12
	v_sub_f32_e32 v10, 1.0, v10
	v_max_f32_e32 v10, 0, v10
	v_cmp_gt_f32_e32 vcc, s31, v10
	v_mul_f32_e32 v14, 0x4f800000, v10
	ds_write_b32 v37, v12 offset:54272
	v_cndmask_b32_e32 v10, v10, v14, vcc
	v_sqrt_f32_e32 v14, v10
	s_nop 0
	v_add_u32_e32 v15, -1, v14
	v_fma_f32 v16, -v15, v14, v10
	v_cmp_ge_f32_e64 s[38:39], 0, v16
	v_add_u32_e32 v16, 1, v14
	s_nop 0
	v_cndmask_b32_e64 v15, v14, v15, s[38:39]
	v_fma_f32 v14, -v16, v14, v10
	v_cmp_lt_f32_e64 s[38:39], 0, v14
	s_nop 1
	v_cndmask_b32_e64 v14, v15, v16, s[38:39]
	ds_read_u16 v16, v31 offset:640
	v_mul_f32_e32 v15, 0x37800000, v14
	v_cndmask_b32_e32 v14, v14, v15, vcc
	v_fma_f32 v15, v39, v46, v0
	v_cmp_class_f32_e32 vcc, v10, v56
	v_fmac_f32_e32 v15, v40, v47
	v_fmac_f32_e32 v15, v42, v44
	v_cndmask_b32_e32 v10, v14, v10, vcc
	s_waitcnt lgkmcnt(0)
; __device__ __forceinline__ float bf2f(bf16_t b) { return __uint_as_float(((unsigned)b) << 16); }
; __device__ __forceinline__ float sigmoidf_(float x) { return frcp(1.0f + fexp2(-x * LOG2E)); }
; template <int APPLY>
; __device__ void lru_item(PP p, int l, int bb, int ck, int nb, unsigned epoch) {
;     ...
;   {
;     bf16x8 a[2];
; #pragma unroll
;     for (int ks = 0; ks < 2; ++ks) a[ks] = *(const bf16x8*)(xcs + (wid * 16 + fr) * 72 + ks * 32 + fq * 8);
; #pragma unroll
;     for (int nk = 0; nk < 4; ++nk) {
;       f32x4 ra = f32x4{0.f, 0.f, 0.f, 0.f}, ia = f32x4{0.f, 0.f, 0.f, 0.f};
; #pragma unroll
;       for (int ks = 0; ks < 2; ++ks) {
;         bf16x8 ba = *(const bf16x8*)(wta + (nk * 16 + fr) * 72 + ks * 32 + fq * 8);
;         bf16x8 bx = *(const bf16x8*)(wtx + (nk * 16 + fr) * 72 + ks * 32 + fq * 8);
;         ra = __builtin_amdgcn_mfma_f32_16x16x32_bf16(a[ks], ba, ra, 0, 0, 0);
;         ia = __builtin_amdgcn_mfma_f32_16x16x32_bf16(a[ks], bx, ia, 0, 0, 0);
;       }
;       const int ch = nk * 16 + fr, gch = nb * 64 + ch;
;       const float ba_ = p->lru_b_a[l * 512 + gch], bx_ = p->lru_b_x[l * 512 + gch];
;       const float sp = log1pf(__expf(-p->lru_lambda[l * 512 + gch]));
;       const float* cw = p->conv_w + (long)l * 4 * 512 + gch;
;       const float w0 = cw[0], w1 = cw[512], w2 = cw[1024], w3 = cw[1536], cb = p->conv_b[l * 512 + gch];
; #pragma unroll
;       for (int reg = 0; reg < 4; ++reg) {
;         const int tok = wid * 16 + 4 * fq + reg;
;         const float r = sigmoidf_(ra[reg] + ba_), ig = sigmoidf_(ia[reg] + bx_);
;         const float log_a = -8.0f * r * sp;
;         const float av = __expf(log_a);
;         const float mult = sqrtf(fmaxf(1.0f - __expf(2.0f * log_a), 0.f));
;         const float xc = cb + w0 * bf2f(cxs[(tok + 0) * 64 + ch]) + w1 * bf2f(cxs[(tok + 1) * 64 + ch]) +
;                          w2 * bf2f(cxs[(tok + 2) * 64 + ch]) + w3 * bf2f(cxs[(tok + 3) * 64 + ch]);
;         as_[tok * 64 + ch] = av;
;         bs_[tok * 64 + ch] = mult * ig * xc;
;       }
;     }
;   }
	v_lshlrev_b32_e32 v16, 16, v16
	v_or_b32_e32 v14, v32, v30
	v_fmac_f32_e32 v15, v41, v16
	v_mul_f32_e32 v10, v11, v10
	v_mul_f32_e32 v10, v15, v10
	v_lshl_add_u32 v11, v14, 2, s4
	ds_write_b32 v11, v10
	v_add_f32_e32 v10, v17, v29
	v_mul_f32_e32 v10, 0xbfb8aa3b, v10
	v_exp_f32_e32 v10, v10
	v_add_f32_e32 v11, v13, v28
	v_mul_f32_e32 v11, 0xbfb8aa3b, v11
	v_exp_f32_e32 v11, v11
	v_add_f32_e32 v10, 1.0, v10
	v_rcp_f32_e32 v10, v10
	v_add_f32_e32 v11, 1.0, v11
	v_rcp_f32_e32 v11, v11
	v_mul_f32_e32 v10, 0xc1000000, v10
	v_mul_f32_e32 v10, v10, v33
	v_mul_f32_e32 v12, 0x3fb8aa3b, v10
	v_add_f32_e32 v10, v10, v10
	v_mul_f32_e32 v10, 0x3fb8aa3b, v10
	v_exp_f32_e32 v10, v10
	v_exp_f32_e32 v12, v12
	v_or_b32_e32 v33, 0xc0, v38
	v_sub_f32_e32 v10, 1.0, v10
	v_max_f32_e32 v10, 0, v10
	v_cmp_gt_f32_e32 vcc, s31, v10
	v_mul_f32_e32 v13, 0x4f800000, v10
	ds_write_b32 v37, v12 offset:54528
	v_cndmask_b32_e32 v10, v10, v13, vcc
	v_sqrt_f32_e32 v13, v10
	s_nop 0
	v_add_u32_e32 v14, -1, v13
	v_fma_f32 v15, -v14, v13, v10
	v_cmp_ge_f32_e64 s[38:39], 0, v15
	v_add_u32_e32 v15, 1, v13
	s_nop 0
	v_cndmask_b32_e64 v14, v13, v14, s[38:39]
	v_fma_f32 v13, -v15, v13, v10
	v_cmp_lt_f32_e64 s[38:39], 0, v13
	s_nop 1
	v_cndmask_b32_e64 v13, v14, v15, s[38:39]
	v_mul_f32_e32 v14, 0x37800000, v13
	v_cndmask_b32_e32 v13, v13, v14, vcc
	ds_read_u16 v14, v31 offset:384
	v_cmp_class_f32_e32 vcc, v10, v56
	s_waitcnt lgkmcnt(0)
	v_lshlrev_b32_e32 v14, 16, v14
	v_fmac_f32_e32 v0, v39, v14
	ds_read_u16 v14, v31 offset:768
	v_fmac_f32_e32 v0, v40, v44
	v_cndmask_b32_e32 v10, v13, v10, vcc
	v_fmac_f32_e32 v0, v42, v16
	v_or_b32_e32 v13, v33, v30
	s_waitcnt lgkmcnt(0)
	v_lshlrev_b32_e32 v14, 16, v14
	v_fmac_f32_e32 v0, v41, v14
	v_mul_f32_e32 v10, v11, v10
	v_mul_f32_e32 v0, v0, v10
	v_lshl_add_u32 v10, v13, 2, s4
	v_or_b32_e32 v40, 16, v30
	ds_write_b32 v10, v0
	v_mul_u32_u24_e32 v0, 0x48, v40
	v_lshl_add_u32 v0, v0, 1, v34
	ds_read_b128 v[10:13], v0 offset:35328
	ds_read_b128 v[14:17], v0 offset:44544
	s_waitcnt lgkmcnt(0)
	v_mfma_f32_16x16x32_bf16 v[42:45], v[6:9], v[14:17], 0
	ds_read_b128 v[14:17], v0 offset:35392
	ds_read_b128 v[46:49], v0 offset:44608
	v_add_u32_e32 v0, s89, v30
	v_add_lshl_u32 v39, v0, s60, 2
	v_mfma_f32_16x16x32_bf16 v[10:13], v[6:9], v[10:13], 0
	v_lshlrev_b32_e32 v0, 2, v0
	s_waitcnt lgkmcnt(1)
	v_mfma_f32_16x16x32_bf16 v[14:17], v[2:5], v[14:17], v[10:13]
	s_waitcnt lgkmcnt(0)
	v_mfma_f32_16x16x32_bf16 v[10:13], v[2:5], v[46:49], v[42:45]
	s_nop 2
	global_load_dword v42, v39, s[56:57] offset:64
	global_load_dword v41, v39, s[48:49] offset:64
	global_load_dword v28, v39, s[50:51] offset:64
	s_waitcnt vmcnt(2)
	v_add_f32_e32 v14, v14, v42
	v_mul_f32_e32 v14, 0xbfb8aa3b, v14
	s_waitcnt vmcnt(0)
	v_exp_f32_e32 v14, v14
	v_add_f32_e32 v10, v10, v41
	v_mul_f32_e32 v10, 0xbfb8aa3b, v10
	v_add_f32_e32 v14, 1.0, v14
	global_load_dword v44, v0, s[40:41] offset:64
	global_load_dword v45, v0, s[40:41] offset:2112
	v_rcp_f32_e32 v14, v14
	v_exp_f32_e32 v10, v10
	v_mul_f32_e32 v14, 0xc1000000, v14
	v_add_f32_e32 v10, 1.0, v10
	v_mov_b32_e32 v48, v28
	v_lshl_add_u64 v[28:29], s[40:41], 0, v[0:1]
	v_add_co_u32_e32 v28, vcc, s6, v28
	v_mul_f32_e32 v49, v14, v48
	s_nop 0
	v_addc_co_u32_e32 v29, vcc, 0, v29, vcc
	global_load_dword v47, v[28:29], off offset:64
	global_load_dword v46, v[28:29], off offset:2112
	global_load_dword v43, v39, s[46:47] offset:64
	v_mul_f32_e32 v14, 0x3fb8aa3b, v49
	v_add_f32_e32 v49, v49, v49
	v_mul_f32_e32 v49, 0x3fb8aa3b, v49
	v_exp_f32_e32 v49, v49
	ds_read_u16 v53, v31 offset:288
	ds_read_u16 v54, v31 offset:416
	v_rcp_f32_e32 v10, v10
	v_sub_f32_e32 v49, 1.0, v49
	v_max_f32_e32 v49, 0, v49
	v_cmp_gt_f32_e32 vcc, s31, v49
	v_mul_f32_e32 v50, 0x4f800000, v49
	v_exp_f32_e32 v14, v14
	v_cndmask_b32_e32 v49, v49, v50, vcc
	v_sqrt_f32_e32 v50, v49
	s_waitcnt lgkmcnt(1)
	v_lshlrev_b32_e32 v53, 16, v53
	s_waitcnt lgkmcnt(0)
	v_lshlrev_b32_e32 v54, 16, v54
	ds_write_b32 v37, v14 offset:53824
	v_add_u32_e32 v51, -1, v50
	v_fma_f32 v52, -v51, v50, v49
	v_cmp_ge_f32_e64 s[38:39], 0, v52
	v_add_u32_e32 v52, 1, v50
	v_add_f32_e32 v11, v11, v41
	v_cndmask_b32_e64 v51, v50, v51, s[38:39]
	v_fma_f32 v50, -v52, v50, v49
	v_cmp_lt_f32_e64 s[38:39], 0, v50
	v_mul_f32_e32 v11, 0xbfb8aa3b, v11
	v_exp_f32_e32 v11, v11
	v_cndmask_b32_e64 v50, v51, v52, s[38:39]
	v_mul_f32_e32 v51, 0x37800000, v50
	v_cndmask_b32_e32 v50, v50, v51, vcc
	ds_read_u16 v51, v31 offset:32
	ds_read_u16 v52, v31 offset:160
	v_cmp_class_f32_e32 vcc, v49, v56
	v_add_f32_e32 v11, 1.0, v11
	v_rcp_f32_e32 v11, v11
	s_waitcnt lgkmcnt(1)
	v_lshlrev_b32_e32 v51, 16, v51
	s_waitcnt lgkmcnt(0)
	v_lshlrev_b32_e32 v52, 16, v52
	v_cndmask_b32_e32 v50, v50, v49, vcc
	v_or_b32_e32 v49, v38, v40
	v_mul_f32_e32 v10, v10, v50
	v_lshlrev_b32_e32 v14, 2, v49
	v_add_u32_e32 v49, s4, v14
	v_add_u32_e32 v14, 0, v14
	s_waitcnt vmcnt(0)
	v_fma_f32 v51, v44, v51, v43
	v_fmac_f32_e32 v51, v45, v52
	v_fmac_f32_e32 v51, v47, v53
	v_fmac_f32_e32 v51, v46, v54
	v_mul_f32_e32 v10, v51, v10
	ds_write_b32 v49, v10
	v_add_f32_e32 v10, v15, v42
	v_mul_f32_e32 v10, 0xbfb8aa3b, v10
	v_exp_f32_e32 v10, v10
	s_nop 0
	v_add_f32_e32 v10, 1.0, v10
	v_rcp_f32_e32 v10, v10
	s_nop 0
	v_mul_f32_e32 v10, 0xc1000000, v10
	v_mul_f32_e32 v10, v10, v48
	v_mul_f32_e32 v15, 0x3fb8aa3b, v10
	v_add_f32_e32 v10, v10, v10
	v_mul_f32_e32 v10, 0x3fb8aa3b, v10
	v_exp_f32_e32 v10, v10
	v_exp_f32_e32 v15, v15
	v_sub_f32_e32 v10, 1.0, v10
	v_max_f32_e32 v10, 0, v10
	v_cmp_gt_f32_e32 vcc, s31, v10
	v_mul_f32_e32 v49, 0x4f800000, v10
	ds_write_b32 v14, v15 offset:54016
	v_cndmask_b32_e32 v10, v10, v49, vcc
	v_sqrt_f32_e32 v49, v10
	s_nop 0
	v_add_u32_e32 v50, -1, v49
	v_fma_f32 v51, -v50, v49, v10
	v_cmp_ge_f32_e64 s[38:39], 0, v51
	v_add_u32_e32 v51, 1, v49
	s_nop 0
	v_cndmask_b32_e64 v50, v49, v50, s[38:39]
	v_fma_f32 v49, -v51, v49, v10
	v_cmp_lt_f32_e64 s[38:39], 0, v49
	s_nop 1
	v_cndmask_b32_e64 v49, v50, v51, s[38:39]
	v_fma_f32 v51, v44, v52, v43
	ds_read_u16 v52, v31 offset:544
	v_mul_f32_e32 v50, 0x37800000, v49
	v_cndmask_b32_e32 v49, v49, v50, vcc
	v_cmp_class_f32_e32 vcc, v10, v56
	v_fmac_f32_e32 v51, v45, v53
	v_fmac_f32_e32 v51, v47, v54
	v_cndmask_b32_e32 v10, v49, v10, vcc
	s_waitcnt lgkmcnt(0)
; __device__ __forceinline__ float bf2f(bf16_t b) { return __uint_as_float(((unsigned)b) << 16); }
; __device__ __forceinline__ float sigmoidf_(float x) { return frcp(1.0f + fexp2(-x * LOG2E)); }
; template <int APPLY>
; __device__ void lru_item(PP p, int l, int bb, int ck, int nb, unsigned epoch) {
;     ...
;   {
;     bf16x8 a[2];
; #pragma unroll
;     for (int ks = 0; ks < 2; ++ks) a[ks] = *(const bf16x8*)(xcs + (wid * 16 + fr) * 72 + ks * 32 + fq * 8);
; #pragma unroll
;     for (int nk = 0; nk < 4; ++nk) {
;       f32x4 ra = f32x4{0.f, 0.f, 0.f, 0.f}, ia = f32x4{0.f, 0.f, 0.f, 0.f};
; #pragma unroll
;       for (int ks = 0; ks < 2; ++ks) {
;         bf16x8 ba = *(const bf16x8*)(wta + (nk * 16 + fr) * 72 + ks * 32 + fq * 8);
;         bf16x8 bx = *(const bf16x8*)(wtx + (nk * 16 + fr) * 72 + ks * 32 + fq * 8);
;         ra = __builtin_amdgcn_mfma_f32_16x16x32_bf16(a[ks], ba, ra, 0, 0, 0);
;         ia = __builtin_amdgcn_mfma_f32_16x16x32_bf16(a[ks], bx, ia, 0, 0, 0);
;       }
;       const int ch = nk * 16 + fr, gch = nb * 64 + ch;
;       const float ba_ = p->lru_b_a[l * 512 + gch], bx_ = p->lru_b_x[l * 512 + gch];
;       const float sp = log1pf(__expf(-p->lru_lambda[l * 512 + gch]));
;       const float* cw = p->conv_w + (long)l * 4 * 512 + gch;
;       const float w0 = cw[0], w1 = cw[512], w2 = cw[1024], w3 = cw[1536], cb = p->conv_b[l * 512 + gch];
; #pragma unroll
;       for (int reg = 0; reg < 4; ++reg) {
;         const int tok = wid * 16 + 4 * fq + reg;
;         const float r = sigmoidf_(ra[reg] + ba_), ig = sigmoidf_(ia[reg] + bx_);
;         const float log_a = -8.0f * r * sp;
;         const float av = __expf(log_a);
;         const float mult = sqrtf(fmaxf(1.0f - __expf(2.0f * log_a), 0.f));
;         const float xc = cb + w0 * bf2f(cxs[(tok + 0) * 64 + ch]) + w1 * bf2f(cxs[(tok + 1) * 64 + ch]) +
;                          w2 * bf2f(cxs[(tok + 2) * 64 + ch]) + w3 * bf2f(cxs[(tok + 3) * 64 + ch]);
;         as_[tok * 64 + ch] = av;
;         bs_[tok * 64 + ch] = mult * ig * xc;
;       }
;     }
;   }
	v_lshlrev_b32_e32 v52, 16, v52
	v_or_b32_e32 v49, v36, v40
	v_fmac_f32_e32 v51, v46, v52
	v_mul_f32_e32 v10, v11, v10
	v_mul_f32_e32 v10, v51, v10
	v_lshl_add_u32 v11, v49, 2, s4
	ds_write_b32 v11, v10
	v_add_f32_e32 v10, v16, v42
	v_mul_f32_e32 v10, 0xbfb8aa3b, v10
	v_exp_f32_e32 v10, v10
	v_add_f32_e32 v11, v12, v41
	v_mul_f32_e32 v11, 0xbfb8aa3b, v11
	v_exp_f32_e32 v11, v11
	v_add_f32_e32 v10, 1.0, v10
	v_rcp_f32_e32 v10, v10
	v_lshl_add_u32 v50, v40, 1, v35
	v_add_f32_e32 v11, 1.0, v11
	v_rcp_f32_e32 v11, v11
	v_mul_f32_e32 v10, 0xc1000000, v10
	v_mul_f32_e32 v10, v10, v48
	v_mul_f32_e32 v12, 0x3fb8aa3b, v10
	v_add_f32_e32 v10, v10, v10
	v_mul_f32_e32 v10, 0x3fb8aa3b, v10
	v_exp_f32_e32 v10, v10
	v_exp_f32_e32 v12, v12
	v_sub_f32_e32 v10, 1.0, v10
	v_max_f32_e32 v10, 0, v10
	v_cmp_gt_f32_e32 vcc, s31, v10
	v_mul_f32_e32 v15, 0x4f800000, v10
	ds_write_b32 v14, v12 offset:54272
	v_cndmask_b32_e32 v10, v10, v15, vcc
	v_sqrt_f32_e32 v15, v10
	s_nop 0
	v_add_u32_e32 v16, -1, v15
	v_fma_f32 v49, -v16, v15, v10
	v_cmp_ge_f32_e64 s[38:39], 0, v49
	v_add_u32_e32 v49, 1, v15
	s_nop 0
	v_cndmask_b32_e64 v16, v15, v16, s[38:39]
	v_fma_f32 v15, -v49, v15, v10
	v_cmp_lt_f32_e64 s[38:39], 0, v15
	s_nop 1
	v_cndmask_b32_e64 v15, v16, v49, s[38:39]
	ds_read_u16 v49, v31 offset:672
	v_mul_f32_e32 v16, 0x37800000, v15
	v_cndmask_b32_e32 v15, v15, v16, vcc
	v_fma_f32 v16, v44, v53, v43
	v_cmp_class_f32_e32 vcc, v10, v56
	v_fmac_f32_e32 v16, v45, v54
	v_fmac_f32_e32 v16, v47, v52
	v_cndmask_b32_e32 v10, v15, v10, vcc
	s_waitcnt lgkmcnt(0)
	v_lshlrev_b32_e32 v49, 16, v49
	v_or_b32_e32 v15, v32, v40
	v_fmac_f32_e32 v16, v46, v49
	v_mul_f32_e32 v10, v11, v10
	v_mul_f32_e32 v10, v16, v10
	v_lshl_add_u32 v11, v15, 2, s4
	ds_write_b32 v11, v10
	v_add_f32_e32 v10, v17, v42
	v_mul_f32_e32 v10, 0xbfb8aa3b, v10
	v_exp_f32_e32 v10, v10
	v_add_f32_e32 v11, v13, v41
	v_mul_f32_e32 v11, 0xbfb8aa3b, v11
	v_exp_f32_e32 v11, v11
	v_add_f32_e32 v10, 1.0, v10
	v_rcp_f32_e32 v10, v10
	v_add_f32_e32 v11, 1.0, v11
	v_rcp_f32_e32 v11, v11
	v_mul_f32_e32 v10, 0xc1000000, v10
	v_mul_f32_e32 v10, v10, v48
	v_mul_f32_e32 v12, 0x3fb8aa3b, v10
	v_add_f32_e32 v10, v10, v10
	v_mul_f32_e32 v10, 0x3fb8aa3b, v10
	v_exp_f32_e32 v10, v10
	v_exp_f32_e32 v12, v12
	v_sub_f32_e32 v10, 1.0, v10
	v_max_f32_e32 v10, 0, v10
	v_cmp_gt_f32_e32 vcc, s31, v10
	v_mul_f32_e32 v13, 0x4f800000, v10
	ds_write_b32 v14, v12 offset:54528
	v_cndmask_b32_e32 v10, v10, v13, vcc
	v_sqrt_f32_e32 v13, v10
	s_nop 0
	v_add_u32_e32 v15, -1, v13
	v_fma_f32 v16, -v15, v13, v10
	v_cmp_ge_f32_e64 s[38:39], 0, v16
	v_add_u32_e32 v16, 1, v13
	s_nop 0
	v_cndmask_b32_e64 v15, v13, v15, s[38:39]
	v_fma_f32 v13, -v16, v13, v10
	v_cmp_lt_f32_e64 s[38:39], 0, v13
	s_nop 1
	v_cndmask_b32_e64 v13, v15, v16, s[38:39]
	v_mul_f32_e32 v15, 0x37800000, v13
	v_cndmask_b32_e32 v13, v13, v15, vcc
	ds_read_u16 v15, v50 offset:384
	v_cmp_class_f32_e32 vcc, v10, v56
	s_waitcnt lgkmcnt(0)
	v_lshlrev_b32_e32 v15, 16, v15
	v_fmac_f32_e32 v43, v44, v15
	ds_read_u16 v15, v31 offset:800
	v_fmac_f32_e32 v43, v45, v52
	v_cndmask_b32_e32 v10, v13, v10, vcc
	v_fmac_f32_e32 v43, v47, v49
	v_or_b32_e32 v13, v33, v40
	s_waitcnt lgkmcnt(0)
	v_lshlrev_b32_e32 v15, 16, v15
	v_fmac_f32_e32 v43, v46, v15
	v_mul_f32_e32 v10, v11, v10
	v_mul_f32_e32 v10, v43, v10
	v_lshl_add_u32 v11, v13, 2, s4
	v_or_b32_e32 v40, 32, v30
	ds_write_b32 v11, v10
	v_mul_u32_u24_e32 v10, 0x48, v40
	v_lshl_add_u32 v41, v10, 1, v34
	ds_read_b128 v[10:13], v41 offset:35328
	ds_read_b128 v[14:17], v41 offset:44544
	s_waitcnt lgkmcnt(0)
	v_mfma_f32_16x16x32_bf16 v[42:45], v[6:9], v[14:17], 0
	ds_read_b128 v[14:17], v41 offset:35392
	ds_read_b128 v[46:49], v41 offset:44608
	v_mfma_f32_16x16x32_bf16 v[10:13], v[6:9], v[10:13], 0
	s_waitcnt lgkmcnt(1)
	v_mfma_f32_16x16x32_bf16 v[14:17], v[2:5], v[14:17], v[10:13]
	s_waitcnt lgkmcnt(0)
	v_mfma_f32_16x16x32_bf16 v[10:13], v[2:5], v[46:49], v[42:45]
	s_nop 2
	global_load_dword v42, v39, s[56:57] offset:128
	global_load_dword v41, v39, s[48:49] offset:128
	global_load_dword v43, v39, s[50:51] offset:128
	s_waitcnt vmcnt(2)
	v_add_f32_e32 v14, v14, v42
	v_mul_f32_e32 v14, 0xbfb8aa3b, v14
	s_waitcnt vmcnt(0)
	v_exp_f32_e32 v14, v14
	v_add_f32_e32 v10, v10, v41
	v_mul_f32_e32 v10, 0xbfb8aa3b, v10
	v_add_f32_e32 v14, 1.0, v14
	v_rcp_f32_e32 v14, v14
	v_exp_f32_e32 v10, v10
	v_mul_f32_e32 v14, 0xc1000000, v14
	v_add_f32_e32 v10, 1.0, v10
	v_rcp_f32_e32 v10, v10
	v_add_f32_e32 v11, v11, v41
	v_mov_b32_e32 v48, v43
	global_load_dword v45, v0, s[40:41] offset:128
	global_load_dword v46, v0, s[40:41] offset:2176
	global_load_dword v47, v[28:29], off offset:128
	global_load_dword v44, v[28:29], off offset:2176
	global_load_dword v43, v39, s[46:47] offset:128
	v_mul_f32_e32 v49, v14, v48
	v_mul_f32_e32 v14, 0x3fb8aa3b, v49
	v_add_f32_e32 v49, v49, v49
	v_mul_f32_e32 v49, 0x3fb8aa3b, v49
	v_exp_f32_e32 v49, v49
	ds_read_u16 v53, v31 offset:320
	ds_read_u16 v54, v31 offset:448
	v_exp_f32_e32 v14, v14
	v_sub_f32_e32 v49, 1.0, v49
	v_max_f32_e32 v49, 0, v49
	v_cmp_gt_f32_e32 vcc, s31, v49
	v_mul_f32_e32 v50, 0x4f800000, v49
	s_waitcnt lgkmcnt(1)
	v_lshlrev_b32_e32 v53, 16, v53
	v_cndmask_b32_e32 v49, v49, v50, vcc
	v_sqrt_f32_e32 v50, v49
	s_waitcnt lgkmcnt(0)
	v_lshlrev_b32_e32 v54, 16, v54
	ds_write_b32 v37, v14 offset:53888
	v_mul_f32_e32 v11, 0xbfb8aa3b, v11
	v_add_u32_e32 v51, -1, v50
	v_fma_f32 v52, -v51, v50, v49
	v_cmp_ge_f32_e64 s[38:39], 0, v52
	v_add_u32_e32 v52, 1, v50
	v_exp_f32_e32 v11, v11
	v_cndmask_b32_e64 v51, v50, v51, s[38:39]
	v_fma_f32 v50, -v52, v50, v49
	v_cmp_lt_f32_e64 s[38:39], 0, v50
	v_add_f32_e32 v11, 1.0, v11
	v_rcp_f32_e32 v11, v11
	v_cndmask_b32_e64 v50, v51, v52, s[38:39]
	v_mul_f32_e32 v51, 0x37800000, v50
	v_cndmask_b32_e32 v50, v50, v51, vcc
	ds_read_u16 v51, v31 offset:64
	ds_read_u16 v52, v31 offset:192
	v_cmp_class_f32_e32 vcc, v49, v56
	s_waitcnt lgkmcnt(1)
; __device__ __forceinline__ float bf2f(bf16_t b) { return __uint_as_float(((unsigned)b) << 16); }
; __device__ __forceinline__ float sigmoidf_(float x) { return frcp(1.0f + fexp2(-x * LOG2E)); }
; template <int APPLY>
; __device__ void lru_item(PP p, int l, int bb, int ck, int nb, unsigned epoch) {
;     ...
;   {
;     bf16x8 a[2];
; #pragma unroll
;     for (int ks = 0; ks < 2; ++ks) a[ks] = *(const bf16x8*)(xcs + (wid * 16 + fr) * 72 + ks * 32 + fq * 8);
; #pragma unroll
;     for (int nk = 0; nk < 4; ++nk) {
;       f32x4 ra = f32x4{0.f, 0.f, 0.f, 0.f}, ia = f32x4{0.f, 0.f, 0.f, 0.f};
; #pragma unroll
;       for (int ks = 0; ks < 2; ++ks) {
;         bf16x8 ba = *(const bf16x8*)(wta + (nk * 16 + fr) * 72 + ks * 32 + fq * 8);
;         bf16x8 bx = *(const bf16x8*)(wtx + (nk * 16 + fr) * 72 + ks * 32 + fq * 8);
;         ra = __builtin_amdgcn_mfma_f32_16x16x32_bf16(a[ks], ba, ra, 0, 0, 0);
;         ia = __builtin_amdgcn_mfma_f32_16x16x32_bf16(a[ks], bx, ia, 0, 0, 0);
;       }
;       const int ch = nk * 16 + fr, gch = nb * 64 + ch;
;       const float ba_ = p->lru_b_a[l * 512 + gch], bx_ = p->lru_b_x[l * 512 + gch];
;       const float sp = log1pf(__expf(-p->lru_lambda[l * 512 + gch]));
;       const float* cw = p->conv_w + (long)l * 4 * 512 + gch;
;       const float w0 = cw[0], w1 = cw[512], w2 = cw[1024], w3 = cw[1536], cb = p->conv_b[l * 512 + gch];
; #pragma unroll
;       for (int reg = 0; reg < 4; ++reg) {
;         const int tok = wid * 16 + 4 * fq + reg;
;         const float r = sigmoidf_(ra[reg] + ba_), ig = sigmoidf_(ia[reg] + bx_);
;         const float log_a = -8.0f * r * sp;
;         const float av = __expf(log_a);
;         const float mult = sqrtf(fmaxf(1.0f - __expf(2.0f * log_a), 0.f));
;         const float xc = cb + w0 * bf2f(cxs[(tok + 0) * 64 + ch]) + w1 * bf2f(cxs[(tok + 1) * 64 + ch]) +
;                          w2 * bf2f(cxs[(tok + 2) * 64 + ch]) + w3 * bf2f(cxs[(tok + 3) * 64 + ch]);
;         as_[tok * 64 + ch] = av;
;         bs_[tok * 64 + ch] = mult * ig * xc;
;       }
;     }
;   }
	v_lshlrev_b32_e32 v51, 16, v51
	s_waitcnt lgkmcnt(0)
	v_lshlrev_b32_e32 v52, 16, v52
	v_cndmask_b32_e32 v50, v50, v49, vcc
	v_or_b32_e32 v49, v38, v40
	v_mul_f32_e32 v10, v10, v50
	v_lshlrev_b32_e32 v14, 2, v49
	v_add_u32_e32 v49, s4, v14
	v_add_u32_e32 v14, 0, v14
	s_waitcnt vmcnt(0)
	v_fma_f32 v51, v45, v51, v43
	v_fmac_f32_e32 v51, v46, v52
	v_fmac_f32_e32 v51, v47, v53
	v_fmac_f32_e32 v51, v44, v54
	v_mul_f32_e32 v10, v51, v10
	ds_write_b32 v49, v10
	v_add_f32_e32 v10, v15, v42
	v_mul_f32_e32 v10, 0xbfb8aa3b, v10
	v_exp_f32_e32 v10, v10
	s_nop 0
	v_add_f32_e32 v10, 1.0, v10
	v_rcp_f32_e32 v10, v10
	s_nop 0
	v_mul_f32_e32 v10, 0xc1000000, v10
	v_mul_f32_e32 v10, v10, v48
	v_mul_f32_e32 v15, 0x3fb8aa3b, v10
	v_add_f32_e32 v10, v10, v10
	v_mul_f32_e32 v10, 0x3fb8aa3b, v10
	v_exp_f32_e32 v10, v10
	v_exp_f32_e32 v15, v15
	v_sub_f32_e32 v10, 1.0, v10
	v_max_f32_e32 v10, 0, v10
	v_cmp_gt_f32_e32 vcc, s31, v10
	v_mul_f32_e32 v49, 0x4f800000, v10
	ds_write_b32 v14, v15 offset:54016
	v_cndmask_b32_e32 v10, v10, v49, vcc
	v_sqrt_f32_e32 v49, v10
	s_nop 0
	v_add_u32_e32 v50, -1, v49
	v_fma_f32 v51, -v50, v49, v10
	v_cmp_ge_f32_e64 s[38:39], 0, v51
	v_add_u32_e32 v51, 1, v49
	s_nop 0
	v_cndmask_b32_e64 v50, v49, v50, s[38:39]
	v_fma_f32 v49, -v51, v49, v10
	v_cmp_lt_f32_e64 s[38:39], 0, v49
	s_nop 1
	v_cndmask_b32_e64 v49, v50, v51, s[38:39]
	v_fma_f32 v51, v45, v52, v43
	ds_read_u16 v52, v31 offset:576
	v_mul_f32_e32 v50, 0x37800000, v49
	v_cndmask_b32_e32 v49, v49, v50, vcc
	v_cmp_class_f32_e32 vcc, v10, v56
	v_fmac_f32_e32 v51, v46, v53
	v_fmac_f32_e32 v51, v47, v54
	v_cndmask_b32_e32 v10, v49, v10, vcc
	s_waitcnt lgkmcnt(0)
	v_lshlrev_b32_e32 v52, 16, v52
	v_or_b32_e32 v49, v36, v40
	v_fmac_f32_e32 v51, v44, v52
	v_mul_f32_e32 v10, v11, v10
	v_mul_f32_e32 v10, v51, v10
	v_lshl_add_u32 v11, v49, 2, s4
	ds_write_b32 v11, v10
	v_add_f32_e32 v10, v16, v42
	v_mul_f32_e32 v10, 0xbfb8aa3b, v10
	v_exp_f32_e32 v10, v10
	v_add_f32_e32 v11, v12, v41
	v_mul_f32_e32 v11, 0xbfb8aa3b, v11
	v_exp_f32_e32 v11, v11
	v_add_f32_e32 v10, 1.0, v10
	v_rcp_f32_e32 v10, v10
	v_lshl_add_u32 v50, v40, 1, v35
	v_add_f32_e32 v11, 1.0, v11
	v_rcp_f32_e32 v11, v11
	v_mul_f32_e32 v10, 0xc1000000, v10
	v_mul_f32_e32 v10, v10, v48
	v_mul_f32_e32 v12, 0x3fb8aa3b, v10
	v_add_f32_e32 v10, v10, v10
	v_mul_f32_e32 v10, 0x3fb8aa3b, v10
	v_exp_f32_e32 v10, v10
	v_exp_f32_e32 v12, v12
	v_sub_f32_e32 v10, 1.0, v10
	v_max_f32_e32 v10, 0, v10
	v_cmp_gt_f32_e32 vcc, s31, v10
	v_mul_f32_e32 v15, 0x4f800000, v10
	ds_write_b32 v14, v12 offset:54272
	v_cndmask_b32_e32 v10, v10, v15, vcc
	v_sqrt_f32_e32 v15, v10
	s_nop 0
	v_add_u32_e32 v16, -1, v15
	v_fma_f32 v49, -v16, v15, v10
	v_cmp_ge_f32_e64 s[38:39], 0, v49
	v_add_u32_e32 v49, 1, v15
	s_nop 0
	v_cndmask_b32_e64 v16, v15, v16, s[38:39]
	v_fma_f32 v15, -v49, v15, v10
	v_cmp_lt_f32_e64 s[38:39], 0, v15
	s_nop 1
	v_cndmask_b32_e64 v15, v16, v49, s[38:39]
	ds_read_u16 v49, v31 offset:704
	v_mul_f32_e32 v16, 0x37800000, v15
	v_cndmask_b32_e32 v15, v15, v16, vcc
	v_fma_f32 v16, v45, v53, v43
	v_cmp_class_f32_e32 vcc, v10, v56
	v_fmac_f32_e32 v16, v46, v54
	v_fmac_f32_e32 v16, v47, v52
	v_cndmask_b32_e32 v10, v15, v10, vcc
	s_waitcnt lgkmcnt(0)
	v_lshlrev_b32_e32 v49, 16, v49
	v_or_b32_e32 v15, v32, v40
	v_fmac_f32_e32 v16, v44, v49
	v_mul_f32_e32 v10, v11, v10
	v_mul_f32_e32 v10, v16, v10
	v_lshl_add_u32 v11, v15, 2, s4
	ds_write_b32 v11, v10
	v_add_f32_e32 v10, v17, v42
	v_mul_f32_e32 v10, 0xbfb8aa3b, v10
	v_exp_f32_e32 v10, v10
	v_add_f32_e32 v11, v13, v41
	v_mul_f32_e32 v11, 0xbfb8aa3b, v11
	v_exp_f32_e32 v11, v11
	v_add_f32_e32 v10, 1.0, v10
	v_rcp_f32_e32 v10, v10
	v_add_f32_e32 v11, 1.0, v11
	v_rcp_f32_e32 v11, v11
	v_mul_f32_e32 v10, 0xc1000000, v10
	v_mul_f32_e32 v10, v10, v48
	v_mul_f32_e32 v12, 0x3fb8aa3b, v10
	v_add_f32_e32 v10, v10, v10
	v_mul_f32_e32 v10, 0x3fb8aa3b, v10
	v_exp_f32_e32 v10, v10
	v_exp_f32_e32 v12, v12
	v_sub_f32_e32 v10, 1.0, v10
	v_max_f32_e32 v10, 0, v10
	v_cmp_gt_f32_e32 vcc, s31, v10
	v_mul_f32_e32 v13, 0x4f800000, v10
	ds_write_b32 v14, v12 offset:54528
	v_cndmask_b32_e32 v10, v10, v13, vcc
	v_sqrt_f32_e32 v13, v10
	s_nop 0
	v_add_u32_e32 v15, -1, v13
	v_fma_f32 v16, -v15, v13, v10
	v_cmp_ge_f32_e64 s[38:39], 0, v16
	v_add_u32_e32 v16, 1, v13
	s_nop 0
	v_cndmask_b32_e64 v15, v13, v15, s[38:39]
	v_fma_f32 v13, -v16, v13, v10
	v_cmp_lt_f32_e64 s[38:39], 0, v13
	s_nop 1
	v_cndmask_b32_e64 v13, v15, v16, s[38:39]
	v_mul_f32_e32 v15, 0x37800000, v13
	v_cndmask_b32_e32 v13, v13, v15, vcc
	ds_read_u16 v15, v50 offset:384
	v_cmp_class_f32_e32 vcc, v10, v56
	s_waitcnt lgkmcnt(0)
	v_lshlrev_b32_e32 v15, 16, v15
	v_fmac_f32_e32 v43, v45, v15
	ds_read_u16 v15, v31 offset:832
	v_fmac_f32_e32 v43, v46, v52
	v_cndmask_b32_e32 v10, v13, v10, vcc
	v_fmac_f32_e32 v43, v47, v49
	v_or_b32_e32 v13, v33, v40
	s_waitcnt lgkmcnt(0)
	v_lshlrev_b32_e32 v15, 16, v15
	v_fmac_f32_e32 v43, v44, v15
	v_mul_f32_e32 v10, v11, v10
	v_mul_f32_e32 v10, v43, v10
	v_lshl_add_u32 v11, v13, 2, s4
	ds_write_b32 v11, v10
	v_or_b32_e32 v11, 48, v30
	v_mul_u32_u24_e32 v10, 0x48, v11
	v_lshl_add_u32 v10, v10, 1, v34
	ds_read_b128 v[12:15], v10 offset:35328
	ds_read_b128 v[40:43], v10 offset:44544
	s_waitcnt lgkmcnt(1)
	v_mfma_f32_16x16x32_bf16 v[12:15], v[6:9], v[12:15], 0
	s_waitcnt lgkmcnt(0)
	v_mfma_f32_16x16x32_bf16 v[40:43], v[6:9], v[40:43], 0
	ds_read_b128 v[6:9], v10 offset:35392
	ds_read_b128 v[44:47], v10 offset:44608
	s_waitcnt lgkmcnt(1)
	v_mfma_f32_16x16x32_bf16 v[6:9], v[2:5], v[6:9], v[12:15]
	s_nop 2
	global_load_dword v13, v39, s[56:57] offset:192
	global_load_dword v12, v39, s[48:49] offset:192
	global_load_dword v10, v39, s[50:51] offset:192
	s_waitcnt vmcnt(2)
; __device__ __forceinline__ float bf2f(bf16_t b) { return __uint_as_float(((unsigned)b) << 16); }
; __device__ __forceinline__ float sigmoidf_(float x) { return frcp(1.0f + fexp2(-x * LOG2E)); }
; template <int APPLY>
; __device__ void lru_item(PP p, int l, int bb, int ck, int nb, unsigned epoch) {
;     ...
;       const int ch = nk * 16 + fr, gch = nb * 64 + ch;
;       const float ba_ = p->lru_b_a[l * 512 + gch], bx_ = p->lru_b_x[l * 512 + gch];
;       const float sp = log1pf(__expf(-p->lru_lambda[l * 512 + gch]));
;       const float* cw = p->conv_w + (long)l * 4 * 512 + gch;
;       const float w0 = cw[0], w1 = cw[512], w2 = cw[1024], w3 = cw[1536], cb = p->conv_b[l * 512 + gch];
; #pragma unroll
;       for (int reg = 0; reg < 4; ++reg) {
;         const int tok = wid * 16 + 4 * fq + reg;
;         const float r = sigmoidf_(ra[reg] + ba_), ig = sigmoidf_(ia[reg] + bx_);
;         const float log_a = -8.0f * r * sp;
;         const float av = __expf(log_a);
;         const float mult = sqrtf(fmaxf(1.0f - __expf(2.0f * log_a), 0.f));
;         const float xc = cb + w0 * bf2f(cxs[(tok + 0) * 64 + ch]) + w1 * bf2f(cxs[(tok + 1) * 64 + ch]) +
;                          w2 * bf2f(cxs[(tok + 2) * 64 + ch]) + w3 * bf2f(cxs[(tok + 3) * 64 + ch]);
;         as_[tok * 64 + ch] = av;
;         bs_[tok * 64 + ch] = mult * ig * xc;
;       }
;     }
;   }
;   __syncthreads();
	s_nop 0
	v_add_f32_e32 v6, v6, v13
	s_waitcnt lgkmcnt(0)
	v_mfma_f32_16x16x32_bf16 v[2:5], v[2:5], v[44:47], v[40:43]
	s_waitcnt vmcnt(0)
	v_mul_f32_e32 v6, 0xbfb8aa3b, v6
	v_exp_f32_e32 v6, v6
	s_nop 0
	v_add_f32_e32 v6, 1.0, v6
	v_rcp_f32_e32 v6, v6
	s_nop 2
	v_add_f32_e32 v2, v2, v12
	v_mul_f32_e32 v6, 0xc1000000, v6
	v_mul_f32_e32 v2, 0xbfb8aa3b, v2
	v_exp_f32_e32 v2, v2
	v_add_f32_e32 v3, v3, v12
	v_mov_b32_e32 v17, v10
	global_load_dword v14, v0, s[40:41] offset:192
	global_load_dword v15, v0, s[40:41] offset:2240
	global_load_dword v16, v[28:29], off offset:192
	global_load_dword v10, v[28:29], off offset:2240
	s_nop 0
	global_load_dword v0, v39, s[46:47] offset:192
	v_mul_f32_e32 v28, v6, v17
	v_mul_f32_e32 v6, 0x3fb8aa3b, v28
	v_add_f32_e32 v28, v28, v28
	v_mul_f32_e32 v28, 0x3fb8aa3b, v28
	v_exp_f32_e32 v28, v28
	ds_read_u16 v39, v31 offset:480
	v_add_f32_e32 v2, 1.0, v2
	v_rcp_f32_e32 v2, v2
	v_sub_f32_e32 v28, 1.0, v28
	v_max_f32_e32 v28, 0, v28
	v_cmp_gt_f32_e32 vcc, s31, v28
	v_mul_f32_e32 v29, 0x4f800000, v28
	v_exp_f32_e32 v6, v6
	v_cndmask_b32_e32 v28, v28, v29, vcc
	v_sqrt_f32_e32 v29, v28
	s_waitcnt lgkmcnt(0)
	v_lshlrev_b32_e32 v39, 16, v39
	ds_write_b32 v37, v6 offset:53952
	v_mul_f32_e32 v3, 0xbfb8aa3b, v3
	v_add_u32_e32 v30, -1, v29
	v_fma_f32 v34, -v30, v29, v28
	v_cmp_ge_f32_e64 s[38:39], 0, v34
	v_add_u32_e32 v34, 1, v29
	v_exp_f32_e32 v3, v3
	v_cndmask_b32_e64 v30, v29, v30, s[38:39]
	v_fma_f32 v29, -v34, v29, v28
	v_cmp_lt_f32_e64 s[38:39], 0, v29
	v_add_f32_e32 v3, 1.0, v3
	v_rcp_f32_e32 v3, v3
	v_cndmask_b32_e64 v29, v30, v34, s[38:39]
	v_mul_f32_e32 v30, 0x37800000, v29
	v_cndmask_b32_e32 v29, v29, v30, vcc
	ds_read_u16 v30, v31 offset:96
	ds_read_u16 v34, v31 offset:224
	v_cmp_class_f32_e32 vcc, v28, v56
	v_add_f32_e32 v4, v4, v12
	v_mul_f32_e32 v4, 0xbfb8aa3b, v4
	v_cndmask_b32_e32 v29, v29, v28, vcc
	v_or_b32_e32 v28, v38, v11
	ds_read_u16 v38, v31 offset:352
	s_waitcnt lgkmcnt(2)
	v_lshlrev_b32_e32 v30, 16, v30
	s_waitcnt lgkmcnt(1)
	v_lshlrev_b32_e32 v34, 16, v34
	v_mul_f32_e32 v2, v2, v29
	v_lshlrev_b32_e32 v6, 2, v28
	s_waitcnt lgkmcnt(0)
	v_lshlrev_b32_e32 v38, 16, v38
	v_add_u32_e32 v28, s4, v6
	v_exp_f32_e32 v4, v4
	s_waitcnt vmcnt(0)
	v_fma_f32 v30, v14, v30, v0
	v_fmac_f32_e32 v30, v15, v34
	v_fmac_f32_e32 v30, v16, v38
	v_fmac_f32_e32 v30, v10, v39
	v_mul_f32_e32 v2, v30, v2
	ds_write_b32 v28, v2
	v_add_f32_e32 v2, v7, v13
	v_mul_f32_e32 v2, 0xbfb8aa3b, v2
	v_exp_f32_e32 v2, v2
	v_fma_f32 v34, v14, v34, v0
	v_fmac_f32_e32 v34, v15, v38
	v_fmac_f32_e32 v34, v16, v39
	v_add_f32_e32 v2, 1.0, v2
	v_rcp_f32_e32 v2, v2
	v_add_f32_e32 v4, 1.0, v4
	v_rcp_f32_e32 v4, v4
	v_mul_f32_e32 v2, 0xc1000000, v2
	v_mul_f32_e32 v2, v2, v17
	v_mul_f32_e32 v7, 0x3fb8aa3b, v2
	v_add_f32_e32 v2, v2, v2
	v_mul_f32_e32 v2, 0x3fb8aa3b, v2
	v_exp_f32_e32 v2, v2
	v_exp_f32_e32 v7, v7
	v_sub_f32_e32 v2, 1.0, v2
	v_max_f32_e32 v2, 0, v2
	v_cmp_gt_f32_e32 vcc, s31, v2
	v_mul_f32_e32 v28, 0x4f800000, v2
	s_nop 0
	v_cndmask_b32_e32 v2, v2, v28, vcc
	v_sqrt_f32_e32 v28, v2
	s_nop 0
	v_add_u32_e32 v29, -1, v28
	v_fma_f32 v30, -v29, v28, v2
	v_cmp_ge_f32_e64 s[38:39], 0, v30
	v_add_u32_e32 v30, 1, v28
	s_nop 0
	v_cndmask_b32_e64 v29, v28, v29, s[38:39]
	v_fma_f32 v28, -v30, v28, v2
	v_cmp_lt_f32_e64 s[38:39], 0, v28
	s_nop 1
	v_cndmask_b32_e64 v28, v29, v30, s[38:39]
	v_mul_f32_e32 v29, 0x37800000, v28
	v_cndmask_b32_e32 v28, v28, v29, vcc
	v_cmp_class_f32_e32 vcc, v2, v56
	v_lshl_add_u32 v30, v11, 1, v35
	v_or_b32_e32 v29, v36, v11
	v_cndmask_b32_e32 v28, v28, v2, vcc
	ds_read_u16 v2, v31 offset:608
	v_mul_f32_e32 v3, v3, v28
	s_waitcnt lgkmcnt(0)
	v_lshlrev_b32_e32 v35, 16, v2
	v_fmac_f32_e32 v34, v10, v35
	v_add_u32_e32 v2, 0, v6
	v_mul_f32_e32 v3, v34, v3
	v_lshl_add_u32 v6, v29, 2, s4
	ds_write_b32 v2, v7 offset:54016
	ds_write_b32 v6, v3
	v_add_f32_e32 v3, v8, v13
	v_mul_f32_e32 v3, 0xbfb8aa3b, v3
	v_exp_f32_e32 v3, v3
	s_nop 0
	v_add_f32_e32 v3, 1.0, v3
	v_rcp_f32_e32 v3, v3
	s_nop 0
	v_mul_f32_e32 v3, 0xc1000000, v3
	v_mul_f32_e32 v3, v3, v17
	v_mul_f32_e32 v6, 0x3fb8aa3b, v3
	v_add_f32_e32 v3, v3, v3
	v_mul_f32_e32 v3, 0x3fb8aa3b, v3
	v_exp_f32_e32 v3, v3
	v_exp_f32_e32 v6, v6
	v_sub_f32_e32 v3, 1.0, v3
	v_max_f32_e32 v3, 0, v3
	v_cmp_gt_f32_e32 vcc, s31, v3
	v_mul_f32_e32 v7, 0x4f800000, v3
	ds_write_b32 v2, v6 offset:54272
	v_cndmask_b32_e32 v3, v3, v7, vcc
	v_sqrt_f32_e32 v7, v3
	s_nop 0
	v_add_u32_e32 v8, -1, v7
	v_fma_f32 v28, -v8, v7, v3
	v_cmp_ge_f32_e64 s[38:39], 0, v28
	v_add_u32_e32 v28, 1, v7
	s_nop 0
	v_cndmask_b32_e64 v8, v7, v8, s[38:39]
	v_fma_f32 v7, -v28, v7, v3
	v_cmp_lt_f32_e64 s[38:39], 0, v7
	s_nop 1
	v_cndmask_b32_e64 v7, v8, v28, s[38:39]
	ds_read_u16 v28, v31 offset:736
	v_mul_f32_e32 v8, 0x37800000, v7
	v_cndmask_b32_e32 v7, v7, v8, vcc
	v_fma_f32 v8, v14, v38, v0
	v_cmp_class_f32_e32 vcc, v3, v56
	v_fmac_f32_e32 v8, v15, v39
	v_fmac_f32_e32 v8, v16, v35
	v_cndmask_b32_e32 v3, v7, v3, vcc
	s_waitcnt lgkmcnt(0)
	v_lshlrev_b32_e32 v28, 16, v28
	v_or_b32_e32 v7, v32, v11
	v_fmac_f32_e32 v8, v10, v28
	v_mul_f32_e32 v3, v4, v3
	v_mul_f32_e32 v3, v8, v3
	v_lshl_add_u32 v4, v7, 2, s4
	ds_write_b32 v4, v3
	v_add_f32_e32 v3, v9, v13
	v_mul_f32_e32 v3, 0xbfb8aa3b, v3
	v_exp_f32_e32 v3, v3
	s_nop 0
	v_add_f32_e32 v3, 1.0, v3
	v_rcp_f32_e32 v4, v3
	v_add_f32_e32 v3, v5, v12
	v_mul_f32_e32 v3, 0xbfb8aa3b, v3
	v_exp_f32_e32 v3, v3
	v_mul_f32_e32 v4, 0xc1000000, v4
	v_mul_f32_e32 v5, v4, v17
	v_mul_f32_e32 v4, 0x3fb8aa3b, v5
	v_add_f32_e32 v5, v5, v5
	v_mul_f32_e32 v5, 0x3fb8aa3b, v5
	v_exp_f32_e32 v5, v5
	v_add_f32_e32 v3, 1.0, v3
	v_rcp_f32_e32 v3, v3
	v_exp_f32_e32 v4, v4
	v_sub_f32_e32 v5, 1.0, v5
	v_max_f32_e32 v5, 0, v5
	v_cmp_gt_f32_e32 vcc, s31, v5
	v_mul_f32_e32 v6, 0x4f800000, v5
	ds_write_b32 v2, v4 offset:54528
	v_cndmask_b32_e32 v5, v5, v6, vcc
	v_sqrt_f32_e32 v6, v5
	s_nop 0
	v_add_u32_e32 v7, -1, v6
	v_fma_f32 v8, -v7, v6, v5
	v_cmp_ge_f32_e64 s[38:39], 0, v8
	v_add_u32_e32 v8, 1, v6
	s_nop 0
	v_cndmask_b32_e64 v7, v6, v7, s[38:39]
	v_fma_f32 v6, -v8, v6, v5
	v_cmp_lt_f32_e64 s[38:39], 0, v6
	s_nop 1
	v_cndmask_b32_e64 v6, v7, v8, s[38:39]
	v_mul_f32_e32 v7, 0x37800000, v6
	v_cndmask_b32_e32 v6, v6, v7, vcc
	ds_read_u16 v7, v30 offset:384
	v_cmp_class_f32_e32 vcc, v5, v56
	s_waitcnt lgkmcnt(0)
	v_lshlrev_b32_e32 v7, 16, v7
	v_fmac_f32_e32 v0, v14, v7
	ds_read_u16 v7, v31 offset:864
	v_fmac_f32_e32 v0, v15, v35
	v_cndmask_b32_e32 v6, v6, v5, vcc
	v_fmac_f32_e32 v0, v16, v28
	v_or_b32_e32 v5, v33, v11
	s_waitcnt lgkmcnt(0)
	v_lshlrev_b32_e32 v7, 16, v7
	v_fmac_f32_e32 v0, v10, v7
	v_mul_f32_e32 v2, v3, v6
	v_mul_f32_e32 v0, v0, v2
	v_lshl_add_u32 v2, v5, 2, s4
	ds_write_b32 v2, v0
	v_or_b32_e32 v0, v25, v71
	v_lshlrev_b32_e32 v0, 2, v0
	v_add_u32_e32 v73, 0, v0
	v_add_u32_e32 v74, s4, v0
	s_waitcnt lgkmcnt(0)
	s_barrier
; template <int APPLY>
; __device__ void lru_item(PP p, int l, int bb, int ck, int nb, unsigned epoch) {
;     ...
;   {
;     const int ch = tid & 63, seg = tid >> 6;
;     float P = 1.f, hh = 0.f;
; #pragma unroll
;     for (int i = 0; i < 16; ++i) {
;       const int idx = (seg * 16 + i) * 64 + ch;
;       const float a = as_[idx], b = bs_[idx];
;       hh = a * hh + b; P *= a;
;       as_[idx] = P; bs_[idx] = hh;
;     }
;     segA[seg * 64 + ch] = P; segH[seg * 64 + ch] = hh;
;   }
;   __syncthreads();
;   if (APPLY == 2) {
;     unsigned long long* tg = p->lruT + ((long)(bb * 64) * 512 + nb * 64) * 2;
;     if (tid < 64) {
;       const int ch = tid;
;       float hl = 0.f, At = 1.f;
; #pragma unroll
;       for (int sg = 0; sg < 8; ++sg) { const float a = segA[sg * 64 + ch]; hl = a * hl + segH[sg * 64 + ch]; At *= a; }
;       unsigned long long* dst = tg + ((long)ck * 512 + ch) * 2;
;       __hip_atomic_store(dst, ((unsigned long long)epoch << 32) | __float_as_uint(At), __ATOMIC_RELAXED, __HIP_MEMORY_SCOPE_AGENT);
;       __hip_atomic_store(dst + 1, ((unsigned long long)epoch << 32) | __float_as_uint(hl), __ATOMIC_RELAXED, __HIP_MEMORY_SCOPE_AGENT);
	ds_read2st64_b32 v[2:3], v73 offset0:210 offset1:211
	ds_read2st64_b32 v[4:5], v74 offset1:1
	s_lshl_b32 s4, s59, 16
	s_or_b32 s92, s4, s52
	s_lshl_b64 s[4:5], s[92:93], 3
	s_add_u32 s38, s42, s4
	s_waitcnt lgkmcnt(0)
	v_fma_f32 v0, 0, v2, v4
	v_fmac_f32_e32 v5, v0, v3
	ds_write2st64_b32 v74, v0, v5 offset1:1
	v_mul_f32_e32 v4, v2, v3
	ds_read2st64_b32 v[2:3], v73 offset0:212 offset1:213
	ds_read2st64_b32 v[6:7], v74 offset0:2 offset1:3
	s_addc_u32 s39, s43, s5
	v_cmp_gt_i32_e32 vcc, 64, v24
	s_waitcnt lgkmcnt(0)
	v_fma_f32 v0, v5, v2, v6
	v_mul_f32_e32 v2, v4, v2
	v_fmac_f32_e32 v7, v0, v3
	ds_write2st64_b32 v73, v4, v2 offset0:211 offset1:212
	ds_write2st64_b32 v74, v0, v7 offset0:2 offset1:3
	v_mul_f32_e32 v6, v2, v3
	ds_read2st64_b32 v[2:3], v73 offset0:214 offset1:215
	ds_read2st64_b32 v[4:5], v74 offset0:4 offset1:5
	s_waitcnt lgkmcnt(0)
	v_fma_f32 v0, v7, v2, v4
	v_mul_f32_e32 v2, v6, v2
	v_fmac_f32_e32 v5, v0, v3
	ds_write2st64_b32 v73, v6, v2 offset0:213 offset1:214
	ds_write2st64_b32 v74, v0, v5 offset0:4 offset1:5
	v_mul_f32_e32 v4, v2, v3
	ds_read2st64_b32 v[2:3], v73 offset0:216 offset1:217
	ds_read2st64_b32 v[6:7], v74 offset0:6 offset1:7
	s_waitcnt lgkmcnt(0)
	v_fma_f32 v0, v5, v2, v6
	v_mul_f32_e32 v2, v4, v2
	v_fmac_f32_e32 v7, v0, v3
	ds_write2st64_b32 v73, v4, v2 offset0:215 offset1:216
	ds_write2st64_b32 v74, v0, v7 offset0:6 offset1:7
	v_mul_f32_e32 v6, v2, v3
	ds_read2st64_b32 v[2:3], v73 offset0:218 offset1:219
	ds_read2st64_b32 v[4:5], v74 offset0:8 offset1:9
	s_waitcnt lgkmcnt(0)
	v_fma_f32 v0, v7, v2, v4
	v_mul_f32_e32 v2, v6, v2
	v_fmac_f32_e32 v5, v0, v3
	ds_write2st64_b32 v73, v6, v2 offset0:217 offset1:218
	ds_write2st64_b32 v74, v0, v5 offset0:8 offset1:9
	v_mul_f32_e32 v4, v2, v3
	ds_read2st64_b32 v[2:3], v73 offset0:220 offset1:221
	ds_read2st64_b32 v[6:7], v74 offset0:10 offset1:11
	s_waitcnt lgkmcnt(0)
	v_fma_f32 v0, v5, v2, v6
	v_mul_f32_e32 v2, v4, v2
	v_fmac_f32_e32 v7, v0, v3
	ds_write2st64_b32 v73, v4, v2 offset0:219 offset1:220
	ds_write2st64_b32 v74, v0, v7 offset0:10 offset1:11
	v_mul_f32_e32 v6, v2, v3
	ds_read2st64_b32 v[2:3], v73 offset0:222 offset1:223
	ds_read2st64_b32 v[4:5], v74 offset0:12 offset1:13
	s_waitcnt lgkmcnt(0)
	v_fma_f32 v0, v7, v2, v4
	v_mul_f32_e32 v2, v6, v2
	v_fmac_f32_e32 v5, v0, v3
	ds_write2st64_b32 v73, v6, v2 offset0:221 offset1:222
	ds_write2st64_b32 v74, v0, v5 offset0:12 offset1:13
	v_mul_f32_e32 v4, v2, v3
	ds_read2st64_b32 v[2:3], v73 offset0:224 offset1:225
	ds_read2st64_b32 v[6:7], v74 offset0:14 offset1:15
	s_waitcnt lgkmcnt(0)
	v_fma_f32 v0, v5, v2, v6
	v_mul_f32_e32 v2, v4, v2
	ds_write2st64_b32 v73, v4, v2 offset0:223 offset1:224
	v_mul_f32_e32 v2, v2, v3
	v_fmac_f32_e32 v7, v0, v3
	ds_write_b32 v73, v2 offset:57600
	ds_write2st64_b32 v74, v0, v7 offset0:14 offset1:15
	v_lshl_add_u32 v0, v24, 2, 0
	v_add_u32_e32 v76, 0x1d200, v0
	v_add_u32_e32 v75, 0x1da00, v0
	ds_write_b32 v76, v2
	ds_write_b32 v75, v7
	s_waitcnt lgkmcnt(0)
	s_barrier
	s_and_saveexec_b64 s[40:41], vcc
	s_cbranch_execz .LBB0_124
	ds_read2st64_b32 v[2:3], v76 offset1:1
	ds_read2st64_b32 v[4:5], v75 offset1:1
	v_ashrrev_i32_e32 v25, 31, v24
	s_lshl_b32 s92, s58, 9
	s_waitcnt lgkmcnt(0)
	v_fma_f32 v4, 0, v2, v4
	v_fmac_f32_e32 v5, v4, v3
	v_mul_f32_e32 v4, v2, v3
	ds_read2st64_b32 v[2:3], v76 offset0:2 offset1:3
	ds_read2st64_b32 v[6:7], v75 offset0:2 offset1:3
	s_waitcnt lgkmcnt(0)
	v_fma_f32 v5, v5, v2, v6
	v_mul_f32_e32 v2, v4, v2
	v_fmac_f32_e32 v7, v5, v3
	v_mul_f32_e32 v6, v2, v3
	ds_read2st64_b32 v[2:3], v76 offset0:4 offset1:5
	ds_read2st64_b32 v[4:5], v75 offset0:4 offset1:5
	s_waitcnt lgkmcnt(0)
	v_fma_f32 v4, v7, v2, v4
	v_mul_f32_e32 v2, v6, v2
	v_fmac_f32_e32 v5, v4, v3
	v_mul_f32_e32 v4, v2, v3
	ds_read2st64_b32 v[2:3], v76 offset0:6 offset1:7
	ds_read2st64_b32 v[6:7], v75 offset0:6 offset1:7
	s_waitcnt lgkmcnt(0)
	v_fma_f32 v5, v5, v2, v6
	v_mul_f32_e32 v2, v4, v2
	v_fmac_f32_e32 v7, v5, v3
	v_lshl_add_u64 v[4:5], v[24:25], 0, s[92:93]
	v_mul_f32_e32 v2, v2, v3
	v_lshl_add_u64 v[4:5], v[4:5], 4, s[38:39]
	v_mov_b32_e32 v3, s71
	global_store_dwordx2 v[4:5], v[2:3], off sc1
	v_mov_b32_e32 v2, v7
	global_store_dwordx2 v[4:5], v[2:3], off offset:8 sc1

; __device__ __forceinline__ float fexp2(float x) { return __builtin_amdgcn_exp2f(x); }
; __device__ __forceinline__ float flog2(float x) { return __builtin_amdgcn_logf(x); }
; __device__ __forceinline__ float shx(float v, int mask, int lane) { return __int_as_float(__builtin_amdgcn_ds_bpermute((lane ^ mask) << 2, __float_as_int(v))); }
; template <int D, int MODE>
; __device__ void attn_item(PP p, int c, int l, int bb, int qb0, int h0) {
;     ...
;       f32x4 s[2];
; #pragma unroll
;       for (int sub = 0; sub < 2; ++sub) {
;         s[sub] = f32x4{0.f, 0.f, 0.f, 0.f};
; #pragma unroll
;         for (int ks = 0; ks < NKS; ++ks) {
;           bf16x8 a = *(const bf16x8*)(Ks + (g * 32 + sub * 16 + fr) * KP + ks * 32 + fq * 8);
;           s[sub] = __builtin_amdgcn_mfma_f32_16x16x32_bf16(a, qf[ks], s[sub], 0, 0, 0);
;         }
;       }
;       float w[8];
;       if (MODE == 1) {
;         float Lv[8], tot = 0.f; bool vld[8];
; #pragma unroll
;         for (int i = 0; i < 8; ++i) {
;           const int rel = r0 + (i >> 2) * 16 + fq * 4 + (i & 3);
;           vld[i] = !masked || (rel < qi);
;           const float z2 = s[i >> 2][i & 3];
;           const float lv = -(fmaxf(z2, 0.f) + flog2(1.0f + fexp2(-fabsf(z2))));
;           Lv[i] = vld[i] ? lv : 0.f;
;           tot += Lv[i];
;         }
;         tot += shx(tot, 16, lane); tot += shx(tot, 32, lane);
;     ...
;       for (int d = 0; d < NDS; ++d) {
;         const int sw = ((2 * d + (fr >> 3)) & 7) << 3;
;         const bf16_t* vrow = Vt + (d * 16 + fr) * VP;
;         union { uint2 h[2]; bf16x8 v; } a;
;         a.h[0] = *(const uint2*)(vrow + ((g * 32 + 4 * fq) ^ sw)); a.h[1] = *(const uint2*)(vrow + ((g * 32 + 16 + 4 * fq) ^ sw));
.LBB0_171:
	s_xor_b64 s[4:5], s[40:41], -1
	s_or_b64 s[58:59], s[58:59], exec
	s_and_saveexec_b64 s[66:67], s[4:5]
	s_cbranch_execz .LBB0_170
	s_add_i32 s31, s13, s8
	s_sub_i32 s4, s31, 32
	v_cmp_lt_i32_e32 vcc, s4, v95
	s_mov_b64 s[4:5], 0
	s_and_saveexec_b64 s[84:85], vcc
	s_cbranch_execz .LBB0_169
	ds_read_b128 v[64:67], v92
	ds_read_b128 v[68:71], v92 offset:64
	v_add_u32_e32 v93, s8, v109
	s_add_i32 s31, s31, -1
	v_cmp_lt_i32_e64 s[46:47], s31, v80
	s_mov_b32 s4, 0xc3160000
	s_waitcnt lgkmcnt(1)
	v_mfma_f32_16x16x32_bf16 v[64:67], v[64:67], v[48:51], 0
	ds_read_b128 v[112:115], v92 offset:2368
	s_waitcnt lgkmcnt(1)
	v_mfma_f32_16x16x32_bf16 v[68:71], v[68:71], v[52:55], v[64:67]
	s_nop 4
	ds_read_b128 v[64:67], v92 offset:2304
	s_waitcnt lgkmcnt(0)
	v_add_u32_e32 v142, s8, v86
	v_subrev_u32_e32 v143, 32, v142
	v_add_u32_e32 v142, -16, v142
	v_xor_b32_e32 v144, v143, v81
	v_xor_b32_e32 v145, v142, v81
	v_lshl_add_u32 v144, v144, 1, v104
	v_lshl_add_u32 v145, v145, 1, v104
	ds_read_b64 v[126:127], v144 offset:36864
	ds_read_b64 v[128:129], v145 offset:36864
	v_xor_b32_e32 v144, v143, v105
	v_xor_b32_e32 v145, v142, v105
	v_lshl_add_u32 v144, v144, 1, v106
	v_lshl_add_u32 v145, v145, 1, v106
	ds_read_b64 v[130:131], v144 offset:36864
	ds_read_b64 v[132:133], v145 offset:36864
	v_xor_b32_e32 v144, v143, v107
	v_xor_b32_e32 v145, v142, v107
	v_lshl_add_u32 v144, v144, 1, v104
	v_lshl_add_u32 v145, v145, 1, v104
	ds_read_b64 v[134:135], v144 offset:53760
	ds_read_b64 v[136:137], v145 offset:53760
	v_xor_b32_e32 v144, v143, v108
	v_xor_b32_e32 v145, v142, v108
	v_lshl_add_u32 v144, v144, 1, v104
	v_lshl_add_u32 v145, v145, 1, v104
	ds_read_b64 v[138:139], v144 offset:62208
	ds_read_b64 v[140:141], v145 offset:62208
	v_mfma_f32_16x16x32_bf16 v[64:67], v[64:67], v[48:51], 0
	v_exp_f32_e64 v116, -|v69|
	v_exp_f32_e64 v117, -|v70|
	v_add_f32_e32 v116, 1.0, v116
	v_log_f32_e32 v116, v116
	v_add_f32_e32 v117, 1.0, v117
	v_mfma_f32_16x16x32_bf16 v[64:67], v[112:115], v[52:55], v[64:67]
	v_max_f32_e32 v115, v69, v69
	v_log_f32_e32 v117, v117
	v_max_f32_e32 v115, 0, v115
	v_subrev_u32_e32 v112, 32, v93
	v_add_f32_e32 v115, v115, v116
	v_max_f32_e32 v116, v70, v70
	v_cmp_lt_i32_e64 s[42:43], v112, v102
	v_max_f32_e32 v116, 0, v116
	s_or_b64 s[42:43], s[46:47], s[42:43]
	v_add_f32_e32 v116, v116, v117
	v_cndmask_b32_e64 v117, 0, -v116, s[42:43]
	v_exp_f32_e64 v116, -|v71|
	v_exp_f32_e64 v114, -|v68|
	v_cmp_lt_i32_e32 vcc, v112, v97
	v_cmp_lt_i32_e64 s[40:41], v112, v101
	v_add_f32_e32 v116, 1.0, v116
	v_add_f32_e32 v114, 1.0, v114
	v_log_f32_e32 v116, v116
	v_log_f32_e32 v114, v114
	v_cmp_lt_i32_e64 s[44:45], v112, v103
	v_max_f32_e32 v112, v71, v71
	v_max_f32_e32 v113, v68, v68
	v_max_f32_e32 v112, 0, v112
	v_max_f32_e32 v113, 0, v113
	v_add_f32_e32 v112, v112, v116
	v_exp_f32_e64 v116, -|v64|
	s_or_b64 vcc, s[46:47], vcc
	v_add_f32_e32 v113, v113, v114
	v_cndmask_b32_e64 v113, 0, -v113, vcc
	s_or_b64 s[40:41], s[46:47], s[40:41]
	v_add_f32_e32 v114, 0, v113
	v_cndmask_b32_e64 v115, 0, -v115, s[40:41]
	v_add_f32_e32 v114, v115, v114
	s_or_b64 s[44:45], s[46:47], s[44:45]
	v_add_f32_e32 v116, 1.0, v116
	v_add_f32_e32 v114, v117, v114
	v_cndmask_b32_e64 v118, 0, -v112, s[44:45]
	v_log_f32_e32 v116, v116
	v_add_f32_e32 v112, v118, v114
	v_add_u32_e32 v114, -16, v93
	v_cmp_lt_i32_e64 s[48:49], v114, v97
	v_max_f32_e32 v114, v64, v64
	v_max_f32_e32 v114, 0, v114
	v_add_f32_e32 v114, v114, v116
	v_exp_f32_e64 v116, -|v65|
	s_or_b64 s[48:49], s[46:47], s[48:49]
	v_cndmask_b32_e64 v119, 0, -v114, s[48:49]
	v_add_u32_e32 v114, -15, v93
	v_add_f32_e32 v116, 1.0, v116
	v_log_f32_e32 v116, v116
	v_cmp_lt_i32_e64 s[50:51], v114, v97
	v_max_f32_e32 v114, v65, v65
	v_max_f32_e32 v114, 0, v114
	v_add_f32_e32 v114, v114, v116
	v_exp_f32_e64 v116, -|v66|
	s_or_b64 s[50:51], s[46:47], s[50:51]
	v_cndmask_b32_e64 v120, 0, -v114, s[50:51]
	v_add_u32_e32 v114, -14, v93
	v_add_f32_e32 v116, 1.0, v116
	v_log_f32_e32 v116, v116
	v_cmp_lt_i32_e64 s[52:53], v114, v97
	v_max_f32_e32 v114, v66, v66
	v_max_f32_e32 v114, 0, v114
	s_or_b64 s[52:53], s[46:47], s[52:53]
	v_add_f32_e32 v114, v114, v116
	v_cndmask_b32_e64 v121, 0, -v114, s[52:53]
	v_exp_f32_e64 v114, -|v67|
	v_add_u32_e32 v93, -13, v93
	v_cmp_lt_i32_e64 s[56:57], v93, v97
	v_max_f32_e32 v93, v67, v67
	v_add_f32_e32 v114, 1.0, v114
	v_log_f32_e32 v114, v114
	v_add_f32_e32 v112, v112, v119
	v_max_f32_e32 v93, 0, v93
	v_add_f32_e32 v112, v120, v112
	s_or_b64 s[46:47], s[46:47], s[56:57]
	v_add_f32_e32 v93, v93, v114
	v_add_f32_e32 v112, v121, v112
	v_cndmask_b32_e64 v93, 0, -v93, s[46:47]
	v_add_f32_e32 v112, v93, v112
	ds_bpermute_b32 v114, v96, v112
	s_waitcnt lgkmcnt(0)
; template <int D, int MODE>
; __device__ void attn_item(PP p, int c, int l, int bb, int qb0, int h0) {
;     ...
;         union { unsigned u[4]; bf16x8 v; } hi, lo;
; #pragma unroll
;         for (int i = 0; i < 4; ++i) {
;           const unsigned hp = cvt_pk_bf16(Lv[2 * i], Lv[2 * i + 1]);
;           hi.u[i] = hp;
;           lo.u[i] = cvt_pk_bf16(Lv[2 * i] - bflo(hp), Lv[2 * i + 1] - bfhi(hp));
;         }
;         f32x4 cs[2];
; #pragma unroll
;         for (int ss_ = 0; ss_ < 2; ++ss_) {
;           cs[ss_] = f32x4{0.f, 0.f, 0.f, 0.f};
;           cs[ss_] = __builtin_amdgcn_mfma_f32_16x16x32_bf16(uop[ss_], hi.v, cs[ss_], 0, 0, 0);
;           cs[ss_] = __builtin_amdgcn_mfma_f32_16x16x32_bf16(uop[ss_], lo.v, cs[ss_], 0, 0, 0);
;         }
; #pragma unroll
;         for (int i = 0; i < 8; ++i) {
;           const float e = s[i >> 2][i & 3] + cs[i >> 2][i & 3] + R;
;           w[i] = vld[i] ? fexp2(e) : 0.f;
;         }
;         R += tot;
;         wdone = __all(R < -150.0f);
;       } else {
;         float gmax = -1e30f;
; #pragma unroll
;         for (int i = 0; i < 8; ++i) {
;           bool v = true;
;           if (MODE == 0) { const int rel = r0 + (i >> 2) * 16 + fq * 4 + (i & 3); v = (rel <= qi) && (rel > qi - 128); }
;           w[i] = v ? s[i >> 2][i & 3] : -1e30f;
;           gmax = fmaxf(gmax, w[i]);
;         }
;         gmax = fmaxf(gmax, shx(gmax, 16, lane)); gmax = fmaxf(gmax, shx(gmax, 32, lane));
;         const float m_new = fmaxf(m_run, gmax);
;         const float alpha = fexp2(m_run - m_new);
;         float ps = 0.f;
; #pragma unroll
;         for (int i = 0; i < 8; ++i) { w[i] = fexp2(w[i] - m_new); ps += w[i]; }
;         lsum = lsum * alpha + ps;
; #pragma unroll
;         for (int d = 0; d < NDS; ++d) { o[d][0] *= alpha; o[d][1] *= alpha; o[d][2] *= alpha; o[d][3] *= alpha; }
;         m_run = m_new;
;       }
;       union { unsigned u[4]; bf16x8 v; } wb;
; #pragma unroll
;       for (int i = 0; i < 4; ++i) wb.u[i] = cvt_pk_bf16(w[2 * i], w[2 * i + 1]);
; #pragma unroll
;       for (int d = 0; d < NDS; ++d) {
;         const int sw = ((2 * d + (fr >> 3)) & 7) << 3;
;         const bf16_t* vrow = Vt + (d * 16 + fr) * VP;
;         union { uint2 h[2]; bf16x8 v; } a;
;         a.h[0] = *(const uint2*)(vrow + ((g * 32 + 4 * fq) ^ sw)); a.h[1] = *(const uint2*)(vrow + ((g * 32 + 16 + 4 * fq) ^ sw));
	v_add_f32_e32 v124, v112, v114
	v_cvt_pk_bf16_f32 v112, v113, v115
	v_lshlrev_b32_e32 v114, 16, v112
	v_sub_f32_e32 v113, v113, v114
	v_and_b32_e32 v114, 0xffff0000, v112
	v_sub_f32_e32 v114, v115, v114
	v_cvt_pk_bf16_f32 v116, v113, v114
	v_cvt_pk_bf16_f32 v113, v117, v118
	v_lshlrev_b32_e32 v114, 16, v113
	v_and_b32_e32 v115, 0xffff0000, v113
	v_sub_f32_e32 v114, v117, v114
	v_sub_f32_e32 v115, v118, v115
	v_cvt_pk_bf16_f32 v117, v114, v115
	v_cvt_pk_bf16_f32 v114, v119, v120
	v_lshlrev_b32_e32 v115, 16, v114
	v_and_b32_e32 v118, 0xffff0000, v114
	v_sub_f32_e32 v115, v119, v115
	v_sub_f32_e32 v118, v120, v118
	v_cvt_pk_bf16_f32 v118, v115, v118
	v_cvt_pk_bf16_f32 v115, v121, v93
	v_lshlrev_b32_e32 v119, 16, v115
	v_and_b32_e32 v120, 0xffff0000, v115
	v_sub_f32_e32 v119, v121, v119
	v_sub_f32_e32 v93, v93, v120
	v_mfma_f32_16x16x32_bf16 v[120:123], v[60:63], v[112:115], 0
	v_cvt_pk_bf16_f32 v119, v119, v93
	ds_bpermute_b32 v125, v98, v124
	v_mfma_f32_16x16x32_bf16 v[112:115], v[0:3], v[112:115], 0
	v_mfma_f32_16x16x32_bf16 v[112:115], v[0:3], v[116:119], v[112:115]
	v_mfma_f32_16x16x32_bf16 v[120:123], v[60:63], v[116:119], v[120:123]
	s_nop 6
	v_add_f32_e32 v64, v64, v112
	v_add_f32_e32 v64, v110, v64
	v_exp_f32_e32 v64, v64
	v_add_f32_e32 v68, v68, v120
	v_add_f32_e32 v69, v69, v121
	v_add_f32_e32 v68, v110, v68
	v_cndmask_b32_e64 v93, 0, v64, s[48:49]
	v_add_f32_e32 v64, v65, v113
	v_add_f32_e32 v64, v110, v64
	v_exp_f32_e32 v64, v64
	v_add_f32_e32 v69, v110, v69
	v_exp_f32_e32 v68, v68
	v_exp_f32_e32 v69, v69
	v_cndmask_b32_e64 v112, 0, v64, s[50:51]
	v_add_f32_e32 v64, v66, v114
	v_add_f32_e32 v64, v110, v64
	v_exp_f32_e32 v64, v64
	v_add_f32_e32 v70, v70, v122
	v_add_f32_e32 v71, v71, v123
	v_add_f32_e32 v70, v110, v70
	v_cndmask_b32_e64 v113, 0, v64, s[52:53]
	v_add_f32_e32 v64, v67, v115
	v_add_f32_e32 v64, v110, v64
	v_exp_f32_e32 v64, v64
	v_add_f32_e32 v71, v110, v71
	v_exp_f32_e32 v70, v70
	v_exp_f32_e32 v71, v71
	v_cndmask_b32_e32 v68, 0, v68, vcc
	v_cndmask_b32_e64 v69, 0, v69, s[40:41]
	v_cndmask_b32_e64 v67, 0, v64, s[46:47]
	s_waitcnt lgkmcnt(0)
	v_add_f32_e32 v64, v124, v125
	v_add_f32_e32 v110, v110, v64
	v_cvt_pk_bf16_f32 v64, v68, v69
	v_cndmask_b32_e64 v70, 0, v70, s[42:43]
	v_cndmask_b32_e64 v71, 0, v71, s[44:45]
	v_cvt_pk_bf16_f32 v66, v93, v112
	v_cvt_pk_bf16_f32 v65, v70, v71
	v_cvt_pk_bf16_f32 v67, v113, v67
	v_cmp_gt_f32_e32 vcc, s4, v110
	s_cmp_eq_u64 vcc, exec
	s_waitcnt lgkmcnt(0)
	v_mfma_f32_16x16x32_bf16 v[56:59], v[126:129], v[64:67], v[56:59]
	s_waitcnt lgkmcnt(0)
	v_mfma_f32_16x16x32_bf16 v[44:47], v[130:133], v[64:67], v[44:47]
	s_waitcnt lgkmcnt(0)
	v_mfma_f32_16x16x32_bf16 v[40:43], v[134:137], v[64:67], v[40:43]
	s_waitcnt lgkmcnt(0)
	v_mfma_f32_16x16x32_bf16 v[20:23], v[138:141], v[64:67], v[20:23]
	s_cselect_b64 s[4:5], -1, 0
	s_and_b64 s[4:5], s[4:5], exec
	s_branch .LBB0_169

; __device__ __forceinline__ float bflo(unsigned w) { return __uint_as_float(w << 16); }
; __device__ __forceinline__ float bfhi(unsigned w) { return __uint_as_float(w & 0xffff0000u); }
; __device__ __forceinline__ float fexp2(float x) { return __builtin_amdgcn_exp2f(x); }
; __device__ __forceinline__ float siluf_(float x) { return x * sigmoidf_(x); }
; __device__ __forceinline__ float shx(float v, int mask, int lane) { return __int_as_float(__builtin_amdgcn_ds_bpermute((lane ^ mask) << 2, __float_as_int(v))); }
; template <int D, int MODE>
; __device__ void attn_item(PP p, int c, int l, int bb, int qb0, int h0) {
;     ...
;   float inv = 1.0f;
;   if (MODE != 1) {
;     lsum += shx(lsum, 16, lane); lsum += shx(lsum, 32, lane);
;     if (MODE == 0) lsum += fexp2(p->swa_sinks[l * 8 + h] * LOG2E - m_run);
;     inv = 1.0f / lsum;
;   }
; #pragma unroll
;   for (int d = 0; d < NDS; ++d) {
;     const uint2 gv = gvp[d];
;     uint2 pk;
;     pk.x = cvt_pk_bf16(o[d][0] * inv * siluf_(bflo(gv.x)), o[d][1] * inv * siluf_(bfhi(gv.x)));
;     pk.y = cvt_pk_bf16(o[d][2] * inv * siluf_(bflo(gv.y)), o[d][3] * inv * siluf_(bfhi(gv.y)));
;     *(uint2*)(qptr + d * 16 + 4 * fq) = pk;
;   }
.LBB0_191:
	ds_bpermute_b32 v50, v109, v92
	s_mov_b32 s13, 0x3fb8aa3b
	s_add_i32 s5, s5, 1
	s_cmp_eq_u32 s5, 4
	s_waitcnt lgkmcnt(0)
	v_add_f32_e32 v50, v92, v50
	ds_bpermute_b32 v51, v110, v50
	s_waitcnt lgkmcnt(0)
	v_add_f32_e32 v50, v50, v51
	v_mov_b32_e32 v51, v129
	s_waitcnt vmcnt(0)
	v_fma_f32 v51, v51, s13, -v93
	v_exp_f32_e32 v51, v51
	s_nop 0
	v_add_f32_e32 v50, v50, v51
	v_div_scale_f32 v51, s[30:31], v50, v50, 1.0
	v_rcp_f32_e32 v52, v51
	s_nop 0
	v_fma_f32 v53, -v51, v52, 1.0
	v_fmac_f32_e32 v52, v53, v52
	v_div_scale_f32 v53, vcc, 1.0, v50, 1.0
	v_mul_f32_e32 v54, v53, v52
	v_fma_f32 v55, -v51, v54, v53
	v_fmac_f32_e32 v54, v55, v52
	v_fma_f32 v51, -v51, v54, v53
	v_div_fmas_f32 v51, v51, v52, v54
	v_lshlrev_b32_e32 v52, 16, v90
	v_div_fixup_f32 v50, v51, v50, 1.0
	v_mul_f32_e32 v51, 0xbfb8aa3b, v52
	v_exp_f32_e32 v51, v51
	v_and_b32_e32 v53, 0xffff0000, v90
	v_add_f32_e32 v51, 1.0, v51
	v_rcp_f32_e32 v54, v51
	v_pk_mul_f32 v[46:47], v[46:47], v[50:51] op_sel_hi:[1,0]
	v_mul_f32_e32 v51, 0xbfb8aa3b, v53
	v_exp_f32_e32 v51, v51
	s_nop 0
	v_add_f32_e32 v51, 1.0, v51
	v_rcp_f32_e32 v55, v51
	v_pk_mul_f32 v[48:49], v[48:49], v[50:51] op_sel_hi:[1,0]
	v_pk_mul_f32 v[42:43], v[42:43], v[50:51] op_sel_hi:[1,0]
	v_pk_mul_f32 v[44:45], v[44:45], v[50:51] op_sel_hi:[1,0]
	v_pk_mul_f32 v[52:53], v[54:55], v[52:53]
	v_pk_mul_f32 v[38:39], v[38:39], v[50:51] op_sel_hi:[1,0]
	v_pk_mul_f32 v[46:47], v[52:53], v[46:47]
	v_lshlrev_b32_e32 v52, 16, v91
	v_cvt_pk_bf16_f32 v46, v46, v47
	v_mul_f32_e32 v47, 0xbfb8aa3b, v52
	v_exp_f32_e32 v47, v47
	v_and_b32_e32 v53, 0xffff0000, v91
	v_pk_mul_f32 v[40:41], v[40:41], v[50:51] op_sel_hi:[1,0]
	v_pk_mul_f32 v[34:35], v[34:35], v[50:51] op_sel_hi:[1,0]
	v_add_f32_e32 v47, 1.0, v47
	v_rcp_f32_e32 v54, v47
	v_mul_f32_e32 v47, 0xbfb8aa3b, v53
	v_exp_f32_e32 v47, v47
	v_pk_mul_f32 v[36:37], v[36:37], v[50:51] op_sel_hi:[1,0]
	v_add_f32_e32 v47, 1.0, v47
	v_rcp_f32_e32 v55, v47
	s_nop 0
	v_pk_mul_f32 v[52:53], v[54:55], v[52:53]
	s_nop 0
	v_pk_mul_f32 v[48:49], v[52:53], v[48:49]
	s_nop 0
	v_cvt_pk_bf16_f32 v47, v48, v49
	global_store_dwordx2 v[82:83], v[46:47], off
	v_lshlrev_b32_e32 v46, 16, v88
	v_and_b32_e32 v47, 0xffff0000, v88
	v_mul_f32_e32 v48, 0xbfb8aa3b, v46
	v_mul_f32_e32 v49, 0xbfb8aa3b, v47
	v_exp_f32_e32 v48, v48
	v_exp_f32_e32 v49, v49
	v_add_f32_e32 v48, 1.0, v48
	v_add_f32_e32 v49, 1.0, v49
	v_rcp_f32_e32 v48, v48
	v_rcp_f32_e32 v49, v49
	s_nop 0
	v_pk_mul_f32 v[46:47], v[48:49], v[46:47]
	s_nop 0
	v_pk_mul_f32 v[42:43], v[46:47], v[42:43]
	v_lshlrev_b32_e32 v46, 16, v89
	v_cvt_pk_bf16_f32 v42, v42, v43
	v_mul_f32_e32 v43, 0xbfb8aa3b, v46
	v_exp_f32_e32 v43, v43
	v_and_b32_e32 v47, 0xffff0000, v89
	v_add_f32_e32 v43, 1.0, v43
	v_rcp_f32_e32 v48, v43
	v_mul_f32_e32 v43, 0xbfb8aa3b, v47
	v_exp_f32_e32 v43, v43
	s_nop 0
	v_add_f32_e32 v43, 1.0, v43
	v_rcp_f32_e32 v49, v43
	s_nop 0
	v_pk_mul_f32 v[46:47], v[48:49], v[46:47]
	s_nop 0
	v_pk_mul_f32 v[44:45], v[46:47], v[44:45]
	s_nop 0
	v_cvt_pk_bf16_f32 v43, v44, v45
	global_store_dwordx2 v[82:83], v[42:43], off offset:32
	v_lshlrev_b32_e32 v42, 16, v86
	v_and_b32_e32 v43, 0xffff0000, v86
	v_mul_f32_e32 v44, 0xbfb8aa3b, v42
	v_mul_f32_e32 v45, 0xbfb8aa3b, v43
	v_exp_f32_e32 v44, v44
	v_exp_f32_e32 v45, v45
	v_add_f32_e32 v44, 1.0, v44
	v_add_f32_e32 v45, 1.0, v45
	v_rcp_f32_e32 v44, v44
	v_rcp_f32_e32 v45, v45
	s_nop 0
	v_pk_mul_f32 v[42:43], v[44:45], v[42:43]
	s_nop 0
	v_pk_mul_f32 v[38:39], v[42:43], v[38:39]
	v_lshlrev_b32_e32 v42, 16, v87
	v_cvt_pk_bf16_f32 v38, v38, v39
	v_mul_f32_e32 v39, 0xbfb8aa3b, v42
	v_exp_f32_e32 v39, v39
	v_and_b32_e32 v43, 0xffff0000, v87
	v_add_f32_e32 v39, 1.0, v39
	v_rcp_f32_e32 v44, v39
	v_mul_f32_e32 v39, 0xbfb8aa3b, v43
	v_exp_f32_e32 v39, v39
	s_nop 0
	v_add_f32_e32 v39, 1.0, v39
	v_rcp_f32_e32 v45, v39
	s_nop 0
	v_pk_mul_f32 v[42:43], v[44:45], v[42:43]
	s_nop 0
	v_pk_mul_f32 v[40:41], v[42:43], v[40:41]
	s_nop 0
	v_cvt_pk_bf16_f32 v39, v40, v41
	global_store_dwordx2 v[82:83], v[38:39], off offset:64
	v_lshlrev_b32_e32 v38, 16, v84
	v_and_b32_e32 v39, 0xffff0000, v84
	v_mul_f32_e32 v40, 0xbfb8aa3b, v38
	v_mul_f32_e32 v41, 0xbfb8aa3b, v39
	v_exp_f32_e32 v40, v40
	v_exp_f32_e32 v41, v41
	v_add_f32_e32 v40, 1.0, v40
	v_add_f32_e32 v41, 1.0, v41
	v_rcp_f32_e32 v40, v40
	v_rcp_f32_e32 v41, v41
	s_nop 0
	v_pk_mul_f32 v[38:39], v[40:41], v[38:39]
	s_nop 0
	v_pk_mul_f32 v[34:35], v[38:39], v[34:35]
	v_lshlrev_b32_e32 v38, 16, v85
	v_cvt_pk_bf16_f32 v34, v34, v35
	v_mul_f32_e32 v35, 0xbfb8aa3b, v38
	v_exp_f32_e32 v35, v35
	v_and_b32_e32 v39, 0xffff0000, v85
	v_add_f32_e32 v35, 1.0, v35
	v_rcp_f32_e32 v40, v35
	v_mul_f32_e32 v35, 0xbfb8aa3b, v39
	v_exp_f32_e32 v35, v35
	s_nop 0
	v_add_f32_e32 v35, 1.0, v35
	v_rcp_f32_e32 v41, v35
	s_nop 0
	v_pk_mul_f32 v[38:39], v[40:41], v[38:39]
	s_nop 0
	v_pk_mul_f32 v[36:37], v[38:39], v[36:37]
	s_nop 0
	v_cvt_pk_bf16_f32 v35, v36, v37
	global_store_dwordx2 v[82:83], v[34:35], off offset:96
	s_cbranch_scc1 .LBB0_113

; __device__ __forceinline__ float bflo(unsigned w) { return __uint_as_float(w << 16); }
; template <int D, int MODE>
; __device__ void attn_item(PP p, int c, int l, int bb, int qb0, int h0) {
;     ...
;   const int h = h0 + ((MODE == 0) ? sub : 0), qb = qb0 + ((MODE == 2) ? sub : 0);
;   const int qcol = (MODE == 0 ? C_AQ : MODE == 1 ? C_BQ : C_MQ) + h * D;
;   const int gcol = (MODE == 0 ? C_AG : MODE == 1 ? C_BG : C_MG) + h * D;
;   const long rowQ = (long)bb * SEQ + qb * 128 + wid * 16 + fr;
;   bf16_t* qptr = p->proj + rowQ * INW + qcol;
;   const int qi = wid * 16 + fr;
;   int krow0, nk;
;   if (MODE == 2) { krow0 = 0; nk = 256; } else if (qb > 0) { krow0 = qb * 128 - 128; nk = 256; } else { krow0 = 0; nk = 128; }
;   const int cc = tid % TPR, trow = tid / TPR;
;   uint4 kreg[NPK], vreg[NPV][2];
;   bool first = true;
;     ...
;   if (sub == 0) ATTN_ISSUE_LOADS_();
;   uint2 gvp[NDS];
;   {
;     const bf16_t* gp0 = p->proj + rowQ * INW + gcol + 4 * fq;
; #pragma unroll
;     for (int d = 0; d < NDS; ++d) gvp[d] = *(const uint2*)(gp0 + d * 16);
;   }
;   bf16x8 qf[NKS];
;   {
;     float qv[NKS][8]; float ss = 0.f;
; #pragma unroll
;     for (int ks = 0; ks < NKS; ++ks) {
;       uint4 u = *(const uint4*)(qptr + ks * 32 + fq * 8);
;       qv[ks][0] = bflo(u.x); qv[ks][1] = bfhi(u.x); qv[ks][2] = bflo(u.y); qv[ks][3] = bfhi(u.y);
;       qv[ks][4] = bflo(u.z); qv[ks][5] = bfhi(u.z); qv[ks][6] = bflo(u.w); qv[ks][7] = bfhi(u.w);
; #pragma unroll
;       for (int i = 0; i < 8; ++i) ss += qv[ks][i] * qv[ks][i];
;     }
;     float rs = sc;
;     const float* qg = (MODE == 0) ? (p->swa_q_gain + l * 64) : (p->mem_q_gain + l * 128);
;     if (MODE != 1) {
;       ss += shx(ss, 16, lane); ss += shx(ss, 32, lane);
;       rs = rsqrtf(ss * (1.0f / D) + EPS) * sc;
;     ...
; #pragma unroll
;       for (int ps = 0; ps < NPK; ++ps)
;         if (ps * RPP < nk) {
;           uint4 u = kreg[ps];
;           if (MODE != 1) {
;             float f[8] = {bflo(u.x), bfhi(u.x), bflo(u.y), bfhi(u.y), bflo(u.z), bfhi(u.z), bflo(u.w), bfhi(u.w)};
;             float ss = 0.f;
; #pragma unroll
;             for (int i = 0; i < 8; ++i) ss += f[i] * f[i];
; #pragma unroll
;             for (int off = 1; off < TPR; off <<= 1) ss += shx(ss, off, lane);
;             const float rs = rsqrtf(ss * (1.0f / D) + EPS);
.LBB0_197:
	s_add_i32 s13, s5, s4
	s_lshl_b32 s92, s13, 7
	v_lshl_add_u64 v[34:35], v[58:59], 0, s[92:93]
	v_mov_b32_e32 v81, v1
	v_lshl_add_u64 v[82:83], v[34:35], 0, v[0:1]
	v_lshl_add_u64 v[38:39], v[34:35], 0, v[80:81]
	v_mov_b64_e32 v[176:177], v[38:39]
	s_cmp_lg_u32 s5, 0
	s_cbranch_scc1 .Lswa_usepf
	global_load_dwordx2 v[90:91], v[82:83], off offset:1536
	global_load_dwordx2 v[88:89], v[82:83], off offset:1568
	global_load_dwordx2 v[86:87], v[82:83], off offset:1600
	global_load_dwordx2 v[84:85], v[82:83], off offset:1632
	global_load_dwordx4 v[34:37], v[38:39], off
	global_load_dwordx4 v[164:167], v[38:39], off offset:64
	s_branch .Lswa_ld_done
.Lswa_usepf:
	s_waitcnt vmcnt(4)
	v_mov_b64_e32 v[90:91], v[168:169]
	v_mov_b64_e32 v[88:89], v[170:171]
	v_mov_b64_e32 v[86:87], v[172:173]
	v_mov_b64_e32 v[84:85], v[174:175]
	v_mov_b64_e32 v[34:35], v[178:179]
	v_mov_b64_e32 v[36:37], v[180:181]
	v_mov_b64_e32 v[164:165], v[182:183]
	v_mov_b64_e32 v[166:167], v[184:185]
.Lswa_ld_done:
	s_add_i32 s92, s13, s95
	s_lshl_b64 s[30:31], s[92:93], 2
	s_add_u32 s44, s40, s30
	s_addc_u32 s45, s41, s31
	s_andn2_b64 vcc, exec, s[46:47]
	s_waitcnt vmcnt(1)
	v_lshlrev_b32_e32 v92, 16, v34
	v_and_b32_e32 v93, 0xffff0000, v34
	v_lshlrev_b32_e32 v94, 16, v35
	v_and_b32_e32 v95, 0xffff0000, v35
	v_lshlrev_b32_e32 v96, 16, v36
	v_and_b32_e32 v97, 0xffff0000, v36
	v_lshlrev_b32_e32 v98, 16, v37
	v_and_b32_e32 v99, 0xffff0000, v37
	v_pk_mul_f32 v[134:135], v[92:93], v[92:93]
	v_pk_mul_f32 v[132:133], v[94:95], v[94:95]
	v_add_f32_e32 v81, v134, v135
	v_add_f32_e32 v81, v81, v132
	v_pk_mul_f32 v[130:131], v[96:97], v[96:97]
	v_add_f32_e32 v81, v133, v81
	v_add_f32_e32 v81, v130, v81
	v_pk_mul_f32 v[128:129], v[98:99], v[98:99]
	v_add_f32_e32 v81, v131, v81
	v_add_f32_e32 v81, v128, v81
	v_add_f32_e32 v81, v129, v81
	s_waitcnt vmcnt(0)
	v_lshlrev_b32_e32 v100, 16, v164
	v_and_b32_e32 v101, 0xffff0000, v164
	v_lshlrev_b32_e32 v102, 16, v165
	v_and_b32_e32 v103, 0xffff0000, v165
	v_lshlrev_b32_e32 v104, 16, v166
	v_and_b32_e32 v105, 0xffff0000, v166
	v_lshlrev_b32_e32 v106, 16, v167
	v_and_b32_e32 v107, 0xffff0000, v167
	global_load_dwordx4 v[34:37], v[76:77], off offset:144
	global_load_dwordx4 v[38:41], v[76:77], off offset:128
	global_load_dwordx4 v[42:45], v[76:77], off offset:16
	global_load_dwordx4 v[46:49], v[76:77], off
	global_load_dword v129, v1, s[44:45]
	v_pk_mul_f32 v[56:57], v[100:101], v[100:101]
	v_pk_mul_f32 v[54:55], v[102:103], v[102:103]
	v_add_f32_e32 v56, v56, v81
	v_add_f32_e32 v56, v57, v56
	v_add_f32_e32 v54, v54, v56
	v_pk_mul_f32 v[52:53], v[104:105], v[104:105]
	v_add_f32_e32 v54, v55, v54
	v_add_f32_e32 v52, v52, v54
	v_pk_mul_f32 v[50:51], v[106:107], v[106:107]
	v_add_f32_e32 v52, v53, v52
	v_add_f32_e32 v50, v50, v52
	v_add_f32_e32 v50, v51, v50
	ds_bpermute_b32 v51, v109, v50
	s_waitcnt lgkmcnt(0)
	v_add_f32_e32 v81, v50, v51
	ds_bpermute_b32 v128, v110, v81
	s_cbranch_vccnz .LBB0_203
	s_waitcnt lgkmcnt(0)
	s_barrier
	global_load_dwordx4 v[50:53], v[78:79], off offset:16
	global_load_dwordx4 v[54:57], v[78:79], off
	v_lshlrev_b32_e32 v130, 16, v14
	v_and_b32_e32 v131, 0xffff0000, v14
	v_lshlrev_b32_e32 v146, 16, v22
	v_and_b32_e32 v147, 0xffff0000, v22
	v_lshlrev_b32_e32 v132, 16, v15
	v_and_b32_e32 v133, 0xffff0000, v15
	v_pk_mul_f32 v[144:145], v[130:131], v[130:131]
	v_lshlrev_b32_e32 v148, 16, v23
	v_and_b32_e32 v149, 0xffff0000, v23
	v_pk_mul_f32 v[160:161], v[146:147], v[146:147]
	v_pk_mul_f32 v[142:143], v[132:133], v[132:133]
	v_pk_mul_f32 v[158:159], v[148:149], v[148:149]
	v_mov_b32_e32 v162, v160
	v_mov_b32_e32 v163, v144
	v_mov_b32_e32 v144, v161
	v_lshlrev_b32_e32 v134, 16, v16
	v_and_b32_e32 v135, 0xffff0000, v16
	v_lshlrev_b32_e32 v150, 16, v24
	v_and_b32_e32 v151, 0xffff0000, v24
	v_pk_add_f32 v[144:145], v[162:163], v[144:145]
	v_mov_b32_e32 v160, v158
	v_mov_b32_e32 v161, v142
	v_pk_mul_f32 v[140:141], v[134:135], v[134:135]
	v_pk_mul_f32 v[156:157], v[150:151], v[150:151]
	v_pk_add_f32 v[144:145], v[144:145], v[160:161]
	v_mov_b32_e32 v142, v159
	v_lshlrev_b32_e32 v136, 16, v17
	v_and_b32_e32 v137, 0xffff0000, v17
	v_lshlrev_b32_e32 v152, 16, v25
	v_and_b32_e32 v153, 0xffff0000, v25
	v_pk_add_f32 v[142:143], v[142:143], v[144:145]
	v_mov_b32_e32 v144, v156
	v_mov_b32_e32 v145, v140
	v_pk_mul_f32 v[138:139], v[136:137], v[136:137]
	v_pk_mul_f32 v[154:155], v[152:153], v[152:153]
	v_pk_add_f32 v[142:143], v[144:145], v[142:143]
	v_mov_b32_e32 v140, v157
	v_pk_add_f32 v[140:141], v[140:141], v[142:143]
	v_mov_b32_e32 v142, v154
	v_mov_b32_e32 v143, v138
	v_pk_add_f32 v[140:141], v[142:143], v[140:141]
	v_mov_b32_e32 v138, v155
	v_pk_add_f32 v[138:139], v[138:139], v[140:141]
	ds_bpermute_b32 v141, v115, v139
	ds_bpermute_b32 v140, v115, v138
	s_mov_b32 s30, 0x3c800000
	s_mov_b32 s13, 0x800000
	s_mov_b32 s79, 0x800000
	s_waitcnt lgkmcnt(0)
	v_pk_add_f32 v[138:139], v[138:139], v[140:141]
	ds_bpermute_b32 v141, v116, v139
	ds_bpermute_b32 v140, v116, v138
	s_waitcnt lgkmcnt(0)
	v_pk_add_f32 v[138:139], v[138:139], v[140:141]
	ds_bpermute_b32 v141, v117, v139
	ds_bpermute_b32 v140, v117, v138
	s_waitcnt lgkmcnt(0)
	v_pk_add_f32 v[138:139], v[138:139], v[140:141]
	s_nop 0
	v_pk_fma_f32 v[138:139], v[138:139], s[30:31], v[242:243] op_sel_hi:[1,0,0]
	s_nop 0
	v_mul_f32_e32 v140, 0x4b800000, v139
	v_cmp_gt_f32_e32 vcc, s13, v139
	v_mul_f32_e32 v141, 0x4b800000, v138
	v_cmp_gt_f32_e64 s[38:39], s13, v138
	v_cndmask_b32_e32 v139, v139, v140, vcc
	v_rsq_f32_e32 v139, v139
	v_cndmask_b32_e64 v138, v138, v141, s[38:39]
	v_rsq_f32_e32 v140, v138
	v_mul_f32_e32 v138, 0x45800000, v139
	v_cndmask_b32_e32 v138, v139, v138, vcc
	v_mul_f32_e32 v141, 0x45800000, v140
	s_waitcnt vmcnt(1)
; __device__ __forceinline__ float bflo(unsigned w) { return __uint_as_float(w << 16); }
; __device__ __forceinline__ float bfhi(unsigned w) { return __uint_as_float(w & 0xffff0000u); }
; __device__ __forceinline__ float shx(float v, int mask, int lane) { return __int_as_float(__builtin_amdgcn_ds_bpermute((lane ^ mask) << 2, __float_as_int(v))); }
; template <int D, int MODE>
; __device__ void attn_item(PP p, int c, int l, int bb, int qb0, int h0) {
;     ...
; #pragma unroll
;       for (int ps = 0; ps < NPK; ++ps)
;         if (ps * RPP < nk) {
;           uint4 u = kreg[ps];
;           if (MODE != 1) {
;             float f[8] = {bflo(u.x), bfhi(u.x), bflo(u.y), bfhi(u.y), bflo(u.z), bfhi(u.z), bflo(u.w), bfhi(u.w)};
;             float ss = 0.f;
; #pragma unroll
;             for (int i = 0; i < 8; ++i) ss += f[i] * f[i];
; #pragma unroll
;             for (int off = 1; off < TPR; off <<= 1) ss += shx(ss, off, lane);
;             const float rs = rsqrtf(ss * (1.0f / D) + EPS);
; #pragma unroll
;             for (int i = 0; i < 8; ++i) f[i] *= rs * kg[cc * 8 + i];
;             u.x = cvt_pk_bf16(f[0], f[1]); u.y = cvt_pk_bf16(f[2], f[3]); u.z = cvt_pk_bf16(f[4], f[5]); u.w = cvt_pk_bf16(f[6], f[7]);
;           }
;           *(uint4*)(Ks + (ps * RPP + trow) * KP + cc * 8) = u;
	v_pk_mul_f32 v[154:155], v[50:51], v[138:139] op_sel_hi:[1,0]
	s_waitcnt vmcnt(0)
	v_pk_mul_f32 v[142:143], v[54:55], v[138:139] op_sel_hi:[1,0]
	v_pk_mul_f32 v[144:145], v[56:57], v[138:139] op_sel_hi:[1,0]
	v_pk_mul_f32 v[138:139], v[52:53], v[138:139] op_sel_hi:[1,0]
	v_pk_mul_f32 v[130:131], v[142:143], v[130:131]
	v_pk_mul_f32 v[132:133], v[144:145], v[132:133]
	v_pk_mul_f32 v[134:135], v[154:155], v[134:135]
	v_pk_mul_f32 v[136:137], v[138:139], v[136:137]
	v_cndmask_b32_e64 v140, v140, v141, s[38:39]
	v_cvt_pk_bf16_f32 v130, v130, v131
	v_cvt_pk_bf16_f32 v131, v132, v133
	v_cvt_pk_bf16_f32 v132, v134, v135
	v_cvt_pk_bf16_f32 v133, v136, v137
	v_pk_mul_f32 v[156:157], v[54:55], v[140:141] op_sel_hi:[1,0]
	ds_write_b128 v127, v[130:133]
	v_pk_mul_f32 v[132:133], v[56:57], v[140:141] op_sel_hi:[1,0]
	v_pk_mul_f32 v[134:135], v[50:51], v[140:141] op_sel_hi:[1,0]
	v_pk_mul_f32 v[130:131], v[156:157], v[146:147]
	v_pk_mul_f32 v[132:133], v[132:133], v[148:149]
	v_pk_mul_f32 v[134:135], v[134:135], v[150:151]
	v_pk_mul_f32 v[136:137], v[52:53], v[140:141] op_sel_hi:[1,0]
	v_cvt_pk_bf16_f32 v130, v130, v131
	v_pk_mul_f32 v[136:137], v[136:137], v[152:153]
	v_cvt_pk_bf16_f32 v131, v132, v133
	v_cvt_pk_bf16_f32 v132, v134, v135
	v_cndmask_b32_e64 v134, 0, 1, s[42:43]
	v_cvt_pk_bf16_f32 v133, v136, v137
	v_cmp_ne_u32_e64 s[38:39], 1, v134
	s_andn2_b64 vcc, exec, s[42:43]
	ds_write_b128 v127, v[130:133] offset:9216
	s_cbranch_vccnz .LBB0_200
	v_lshlrev_b32_e32 v130, 16, v10
	v_and_b32_e32 v131, 0xffff0000, v10
	v_lshlrev_b32_e32 v146, 16, v6
	v_and_b32_e32 v147, 0xffff0000, v6
	v_lshlrev_b32_e32 v132, 16, v11
	v_and_b32_e32 v133, 0xffff0000, v11
	v_pk_mul_f32 v[144:145], v[130:131], v[130:131]
	v_lshlrev_b32_e32 v148, 16, v7
	v_and_b32_e32 v149, 0xffff0000, v7
	v_pk_mul_f32 v[160:161], v[146:147], v[146:147]
	v_pk_mul_f32 v[142:143], v[132:133], v[132:133]
	v_pk_mul_f32 v[158:159], v[148:149], v[148:149]
	v_mov_b32_e32 v162, v160
	v_mov_b32_e32 v163, v144
	v_mov_b32_e32 v144, v161
	v_lshlrev_b32_e32 v134, 16, v12
	v_and_b32_e32 v135, 0xffff0000, v12
	v_lshlrev_b32_e32 v150, 16, v8
	v_and_b32_e32 v151, 0xffff0000, v8
	v_pk_add_f32 v[144:145], v[162:163], v[144:145]
	v_mov_b32_e32 v160, v158
	v_mov_b32_e32 v161, v142
	v_pk_mul_f32 v[140:141], v[134:135], v[134:135]
	v_pk_mul_f32 v[156:157], v[150:151], v[150:151]
	v_pk_add_f32 v[144:145], v[144:145], v[160:161]
	v_mov_b32_e32 v142, v159
	v_lshlrev_b32_e32 v136, 16, v13
	v_and_b32_e32 v137, 0xffff0000, v13
	v_lshlrev_b32_e32 v152, 16, v9
	v_and_b32_e32 v153, 0xffff0000, v9
	v_pk_add_f32 v[142:143], v[142:143], v[144:145]
	v_mov_b32_e32 v144, v156
	v_mov_b32_e32 v145, v140
	v_pk_mul_f32 v[138:139], v[136:137], v[136:137]
	v_pk_mul_f32 v[154:155], v[152:153], v[152:153]
	v_pk_add_f32 v[142:143], v[144:145], v[142:143]
	v_mov_b32_e32 v140, v157
	v_pk_add_f32 v[140:141], v[140:141], v[142:143]
	v_mov_b32_e32 v142, v154
	v_mov_b32_e32 v143, v138
	v_pk_add_f32 v[140:141], v[142:143], v[140:141]
	v_mov_b32_e32 v138, v155
	v_pk_add_f32 v[138:139], v[138:139], v[140:141]
	ds_bpermute_b32 v141, v115, v139
	ds_bpermute_b32 v140, v115, v138
	s_waitcnt lgkmcnt(0)
	v_pk_add_f32 v[138:139], v[138:139], v[140:141]
	ds_bpermute_b32 v141, v116, v139
	ds_bpermute_b32 v140, v116, v138
	s_waitcnt lgkmcnt(0)
	v_pk_add_f32 v[138:139], v[138:139], v[140:141]
	ds_bpermute_b32 v141, v117, v139
	ds_bpermute_b32 v140, v117, v138
	s_waitcnt lgkmcnt(0)
	v_pk_add_f32 v[138:139], v[138:139], v[140:141]
	s_nop 0
	v_pk_fma_f32 v[138:139], v[138:139], s[30:31], v[242:243] op_sel_hi:[1,0,0]
	s_nop 0
	v_mul_f32_e32 v140, 0x4b800000, v139
	v_cmp_gt_f32_e32 vcc, s13, v139
	s_nop 1
	v_cndmask_b32_e32 v139, v139, v140, vcc
	v_rsq_f32_e32 v139, v139
	s_nop 0
	v_mul_f32_e32 v140, 0x45800000, v139
	v_cndmask_b32_e32 v140, v139, v140, vcc
	v_pk_mul_f32 v[142:143], v[54:55], v[140:141] op_sel_hi:[1,0]
	v_cmp_gt_f32_e32 vcc, s13, v138
	v_pk_mul_f32 v[130:131], v[142:143], v[130:131]
	v_pk_mul_f32 v[142:143], v[56:57], v[140:141] op_sel_hi:[1,0]
	v_cvt_pk_bf16_f32 v130, v130, v131
	v_pk_mul_f32 v[132:133], v[142:143], v[132:133]
	v_pk_mul_f32 v[142:143], v[50:51], v[140:141] op_sel_hi:[1,0]
	v_cvt_pk_bf16_f32 v131, v132, v133
	v_mul_f32_e32 v132, 0x4b800000, v138
	v_cndmask_b32_e32 v132, v138, v132, vcc
	v_rsq_f32_e32 v138, v132
	v_pk_mul_f32 v[140:141], v[52:53], v[140:141] op_sel_hi:[1,0]
	v_pk_mul_f32 v[134:135], v[142:143], v[134:135]
	v_pk_mul_f32 v[136:137], v[140:141], v[136:137]
	v_cvt_pk_bf16_f32 v132, v134, v135
	v_cvt_pk_bf16_f32 v133, v136, v137
	ds_write_b128 v127, v[130:133] offset:18432
	v_mul_f32_e32 v130, 0x45800000, v138
	v_cndmask_b32_e32 v130, v138, v130, vcc
	v_pk_mul_f32 v[50:51], v[50:51], v[130:131] op_sel_hi:[1,0]
	v_pk_mul_f32 v[54:55], v[54:55], v[130:131] op_sel_hi:[1,0]
	v_pk_mul_f32 v[56:57], v[56:57], v[130:131] op_sel_hi:[1,0]
	v_pk_mul_f32 v[132:133], v[50:51], v[150:151]
	v_pk_mul_f32 v[50:51], v[52:53], v[130:131] op_sel_hi:[1,0]
	v_pk_mul_f32 v[54:55], v[54:55], v[146:147]
	v_pk_mul_f32 v[56:57], v[56:57], v[148:149]
	v_pk_mul_f32 v[130:131], v[50:51], v[152:153]
	v_cvt_pk_bf16_f32 v50, v54, v55
	v_cvt_pk_bf16_f32 v51, v56, v57
	v_cvt_pk_bf16_f32 v52, v132, v133
	v_cvt_pk_bf16_f32 v53, v130, v131
	ds_write_b128 v127, v[50:53] offset:27648

; __device__ __forceinline__ float shx(float v, int mask, int lane) { return __int_as_float(__builtin_amdgcn_ds_bpermute((lane ^ mask) << 2, __float_as_int(v))); }
; template <int D, int MODE>
; __device__ void attn_item(PP p, int c, int l, int bb, int qb0, int h0) {
;     ...
;     float rs = sc;
;     const float* qg = (MODE == 0) ? (p->swa_q_gain + l * 64) : (p->mem_q_gain + l * 128);
;     if (MODE != 1) {
;       ss += shx(ss, 16, lane); ss += shx(ss, 32, lane);
;       rs = rsqrtf(ss * (1.0f / D) + EPS) * sc;
;     }
; #pragma unroll
;     for (int ks = 0; ks < NKS; ++ks) {
;       float g[8];
; #pragma unroll
;       for (int i = 0; i < 8; ++i) g[i] = (MODE != 1) ? qg[ks * 32 + fq * 8 + i] * rs : rs;
;       union { unsigned u[4]; bf16x8 v; } cv;
; #pragma unroll
;       for (int i = 0; i < 4; ++i) cv.u[i] = cvt_pk_bf16(qv[ks][2 * i] * g[2 * i], qv[ks][2 * i + 1] * g[2 * i + 1]);
;       qf[ks] = cv.v;
;     }
;   }
;   bf16x8 uop[2];
;   if (MODE == 1) {
;     int onev = 0x3F80; asm volatile("" : "+v"(onev));
; #pragma unroll
;     for (int ss_ = 0; ss_ < 2; ++ss_) {
;       const int srow = ss_ * 16 + fr;
; #pragma unroll
;       for (int i = 0; i < 8; ++i) {
;         const int j = (i < 4) ? (4 * fq + i) : (16 + 4 * fq + (i - 4));
;         uop[ss_][i] = (j >= srow) ? (short)onev : (short)0;
;       }
;     }
;   }
;   f32x4 o[NDS];
; #pragma unroll
;   for (int d = 0; d < NDS; ++d) o[d] = f32x4{0.f, 0.f, 0.f, 0.f};
;   float m_run = -1e30f, lsum = 0.f, R = 0.f;
;   if (MODE == 0) m_run = p->swa_sinks[l * 8 + h] * LOG2E;
.LBB0_203:
	s_waitcnt lgkmcnt(0)
	v_add_f32_e32 v50, v81, v128
	v_fmamk_f32 v50, v50, 0x3c800000, v242
	v_mul_f32_e32 v51, 0x4b800000, v50
	v_cmp_gt_f32_e32 vcc, s79, v50
	s_mov_b32 s13, 0
	v_mov_b32_e32 v81, v125
	v_cndmask_b32_e32 v50, v50, v51, vcc
	v_rsq_f32_e32 v50, v50
	s_mov_b32 s30, s6
	v_mul_f32_e32 v51, 0x45800000, v50
	v_cndmask_b32_e32 v50, v50, v51, vcc
	v_mul_f32_e32 v54, 0x3e38aa3b, v50
	s_waitcnt vmcnt(1)
	v_pk_mul_f32 v[46:47], v[46:47], v[54:55] op_sel_hi:[1,0]
	v_pk_mul_f32 v[42:43], v[42:43], v[54:55] op_sel_hi:[1,0]
	v_pk_mul_f32 v[38:39], v[38:39], v[54:55] op_sel_hi:[1,0]
	v_pk_mul_f32 v[34:35], v[34:35], v[54:55] op_sel_hi:[1,0]
	v_pk_mul_f32 v[48:49], v[48:49], v[54:55] op_sel_hi:[1,0]
	v_pk_mul_f32 v[44:45], v[44:45], v[54:55] op_sel_hi:[1,0]
	v_pk_mul_f32 v[46:47], v[46:47], v[92:93]
	v_pk_mul_f32 v[42:43], v[42:43], v[96:97]
	v_pk_mul_f32 v[40:41], v[40:41], v[54:55] op_sel_hi:[1,0]
	v_pk_mul_f32 v[36:37], v[36:37], v[54:55] op_sel_hi:[1,0]
	v_pk_mul_f32 v[38:39], v[38:39], v[100:101]
	v_pk_mul_f32 v[34:35], v[34:35], v[104:105]
	v_cvt_pk_bf16_f32 v50, v46, v47
	v_pk_mul_f32 v[46:47], v[48:49], v[94:95]
	v_cvt_pk_bf16_f32 v52, v42, v43
	v_pk_mul_f32 v[42:43], v[44:45], v[98:99]
	v_cvt_pk_bf16_f32 v54, v38, v39
	v_pk_mul_f32 v[38:39], v[40:41], v[102:103]
	v_cvt_pk_bf16_f32 v56, v34, v35
	v_pk_mul_f32 v[34:35], v[36:37], v[106:107]
	v_mov_b32_e32 v36, v1
	v_mov_b32_e32 v37, v1
	v_cvt_pk_bf16_f32 v51, v46, v47
	v_cvt_pk_bf16_f32 v53, v42, v43
	v_cvt_pk_bf16_f32 v55, v38, v39
	v_cvt_pk_bf16_f32 v57, v34, v35
	v_mov_b32_e32 v34, v1
	v_mov_b32_e32 v35, v1
	v_mov_b64_e32 v[40:41], v[36:37]
	v_mov_b64_e32 v[44:45], v[36:37]
	v_mov_b64_e32 v[48:49], v[36:37]
	s_waitcnt vmcnt(0)
	v_mul_f32_e32 v93, 0x3fb8aa3b, v129
	v_mov_b32_e32 v92, 0
	v_mov_b64_e32 v[38:39], v[34:35]
	v_mov_b64_e32 v[42:43], v[34:35]
	v_mov_b64_e32 v[46:47], v[34:35]
	s_cmp_gt_u32 s5, 2
	s_cbranch_scc1 .Lswa_nopf
	global_load_dwordx2 v[168:169], v[82:83], off offset:1664
	global_load_dwordx2 v[170:171], v[82:83], off offset:1696
	global_load_dwordx2 v[172:173], v[82:83], off offset:1728
	global_load_dwordx2 v[174:175], v[82:83], off offset:1760
	global_load_dwordx4 v[178:181], v[176:177], off offset:128
	global_load_dwordx4 v[182:185], v[176:177], off offset:192
.Lswa_nopf:
	s_branch .LBB0_205
.LBB0_204:
	s_or_b64 exec, exec, s[46:47]
	s_add_i32 s30, s30, -1
	s_sub_i32 s13, s13, 32
	s_cmp_lt_i32 s30, 2
	v_add_u32_e32 v81, 0xffffee00, v81
	s_cbranch_scc1 .LBB0_191
